# GEMM k-loops: LDS-DMA issued with scalar base + 32-bit lane offset and running scalar pointers (no per-piece 64-bit VALU adds / readfirstlane), 10 of 12 loops
# speedup vs baseline: 1.0200x; 1.0118x over previous
.Lto_j_a0:
	s_mul_i32 s98, s98, 17
	s_add_u32 s98, s98, s99
	s_lshl_b32 s99, s98, 3
	s_or_b32 s99, s99, s84
	s_mul_hi_i32 s6, s98, 0x78787879
	s_lshr_b32 s7, s6, 31
	s_ashr_i32 s6, s6, 3
	s_add_i32 s6, s6, s7
	s_mul_i32 s7, s6, 0xffffffef
	s_add_i32 s7, s7, s98
	s_lshl_b32 s7, s7, 3
	s_or_b32 s8, s7, s84
	v_mov_b32_e32 v0, v174
	s_ashr_i32 s9, s8, 31
	s_lshl_b64 s[10:11], s[8:9], 18
	v_bfe_u32 v2, v0, 1, 3
	v_lshrrev_b32_e32 v3, 4, v0
	v_bfe_u32 v4, v0, 4, 2
	v_lshlrev_b32_e32 v5, 7, v0
	v_and_b32_e32 v6, 0x780, v5
	v_bitop3_b32 v3, v3, v2, 3 bitop3:0x6c
	v_bitop3_b32 v2, v4, v2, 4 bitop3:0x36
	s_add_u32 s10, s38, s10
	v_lshl_or_b32 v7, v3, 4, v6
	v_lshl_or_b32 v6, v2, 4, v6
	v_lshlrev_b32_e32 v2, 6, v0
	s_addc_u32 s11, s39, s11
	s_ashr_i32 s7, s6, 31
	v_lshlrev_b32_e32 v1, 8, v0
	v_and_b32_e32 v8, 0xffffe000, v2
	v_lshlrev_b32_e32 v2, 4, v0
	s_lshl_b64 s[12:13], s[6:7], 18
	v_and_b32_e32 v1, 0xfffff800, v1
	v_xor_b32_e32 v0, v2, v0
	s_movk_i32 s7, 0x70
	v_add_u32_e32 v100, 0, v2
	v_and_or_b32 v64, v0, s7, v1
	v_readfirstlane_b32 s7, v100
	v_add_u32_e32 v101, 0x1000, v100
	s_mov_b32 m0, s7
	v_readfirstlane_b32 s7, v101
	v_add_u32_e32 v102, 0x2000, v100
	global_load_lds_dwordx4 v64, s[10:11]
	v_add_u32_e32 v0, 0x10000, v64
	s_mov_b32 m0, s7
	v_readfirstlane_b32 s7, v102
	v_add_u32_e32 v103, 0x3000, v100
	global_load_lds_dwordx4 v0, s[10:11]
	v_add_u32_e32 v2, 0x20000, v64
	s_mov_b32 m0, s7
	v_readfirstlane_b32 s7, v103
	v_add_u32_e32 v104, 0x4000, v100
	s_add_u32 s12, s36, s12
	global_load_lds_dwordx4 v2, s[10:11]
	v_add_u32_e32 v4, 0x30000, v64
	s_mov_b32 m0, s7
	v_readfirstlane_b32 s7, v104
	v_add_u32_e32 v105, 0x5000, v100
	s_addc_u32 s13, s37, s13
	global_load_lds_dwordx4 v4, s[10:11]
	s_mov_b32 m0, s7
	v_readfirstlane_b32 s7, v105
	v_add_u32_e32 v106, 0x6000, v100
	global_load_lds_dwordx4 v64, s[12:13]
	s_mov_b32 m0, s7
	v_readfirstlane_b32 s7, v106
	v_add_u32_e32 v107, 0x7000, v100
	global_load_lds_dwordx4 v0, s[12:13]
	s_mov_b32 m0, s7
	v_readfirstlane_b32 s7, v107
	global_load_lds_dwordx4 v2, s[12:13]
	s_mov_b32 m0, s7
	s_mul_i32 s7, s6, 0x88
	global_load_lds_dwordx4 v4, s[12:13]
	s_sub_i32 s10, s99, s7
	s_ashr_i32 s11, s10, 31
	s_lshl_b64 s[10:11], s[10:11], 18
	v_and_b32_e32 v9, 0x2000, v5
	s_add_u32 s10, s38, s10
	v_mov_b32_e32 v1, v65
	v_mov_b32_e32 v3, v65
	v_mov_b32_e32 v5, v65
	v_add_u32_e32 v8, 0, v8
	v_add_u32_e32 v9, 0, v9
	s_addc_u32 s11, s39, s11
	v_lshl_add_u64 v[66:67], s[12:13], 0, v[64:65]
	v_lshl_add_u64 v[68:69], s[12:13], 0, v[0:1]
	v_lshl_add_u64 v[70:71], s[12:13], 0, v[2:3]
	v_lshl_add_u64 v[72:73], s[12:13], 0, v[4:5]
	v_lshl_add_u64 v[74:75], s[10:11], 0, v[64:65]
	v_lshl_add_u64 v[76:77], s[10:11], 0, v[0:1]
	v_lshl_add_u64 v[78:79], s[10:11], 0, v[2:3]
	v_lshl_add_u64 v[80:81], s[10:11], 0, v[4:5]
	s_mov_b64 s[10:11], 0
	v_add_u32_e32 v64, 0x8000, v100
	v_add_u32_e32 v108, 0x9000, v100
	v_add_u32_e32 v109, 0xa000, v100
	v_add_u32_e32 v110, 0xb000, v100
	v_add_u32_e32 v111, 0xc000, v100
	v_add_u32_e32 v112, 0xd000, v100
	v_add_u32_e32 v113, 0xe000, v100
	v_add_u32_e32 v114, 0xf000, v100
	v_add_u32_e32 v115, v8, v7
	v_add_u32_e32 v116, v9, v7
	v_add_u32_e32 v117, v8, v6
	v_add_u32_e32 v118, v9, v6
	s_mov_b32 s7, 0
	v_mov_b32_e32 v0, 0
	v_mov_b32_e32 v2, v65
	v_mov_b32_e32 v4, 0
	v_mov_b32_e32 v6, v65
	v_mov_b32_e32 v7, v65
	v_mov_b32_e32 v8, 0
	v_mov_b32_e32 v9, v65
	v_mov_b32_e32 v10, v65
	v_mov_b32_e32 v11, v65
	v_mov_b32_e32 v12, 0
	v_mov_b32_e32 v13, v65
	v_mov_b32_e32 v14, v65
	v_mov_b32_e32 v15, v65
	v_mov_b32_e32 v16, 0
	v_mov_b32_e32 v17, v65
	v_mov_b32_e32 v18, v65
	v_mov_b32_e32 v19, v65
	v_mov_b32_e32 v20, 0
	v_mov_b32_e32 v21, v65
	v_mov_b32_e32 v22, v65
	v_mov_b32_e32 v23, v65
	v_mov_b32_e32 v24, 0
	v_mov_b32_e32 v25, v65
	v_mov_b32_e32 v26, v65
	v_mov_b32_e32 v27, v65
	v_mov_b32_e32 v28, 0
	v_mov_b32_e32 v29, v65
	v_mov_b32_e32 v30, v65
	v_mov_b32_e32 v31, v65
	v_mov_b32_e32 v32, 0
	v_mov_b32_e32 v33, v65
	v_mov_b32_e32 v34, v65
	v_mov_b32_e32 v35, v65
	v_mov_b32_e32 v36, 0
	v_mov_b32_e32 v37, v65
	v_mov_b32_e32 v38, v65
	v_mov_b32_e32 v39, v65
	v_mov_b32_e32 v40, 0
	v_mov_b32_e32 v41, v65
	v_mov_b32_e32 v42, v65
	v_mov_b32_e32 v43, v65
	v_mov_b32_e32 v44, 0
	v_mov_b32_e32 v45, v65
	v_mov_b32_e32 v46, v65
	v_mov_b32_e32 v47, v65
	v_mov_b32_e32 v48, 0
	v_mov_b32_e32 v49, v65
	v_mov_b32_e32 v50, v65
	v_mov_b32_e32 v51, v65
	v_mov_b32_e32 v52, 0
	v_mov_b32_e32 v53, v65
	v_mov_b32_e32 v54, v65
	v_mov_b32_e32 v55, v65
	v_mov_b32_e32 v56, 0
	v_mov_b32_e32 v57, v65
	v_mov_b32_e32 v58, v65
	v_mov_b32_e32 v59, v65
	v_mov_b32_e32 v60, 0
	v_mov_b32_e32 v61, v65
	v_mov_b32_e32 v62, v65
	v_mov_b32_e32 v63, v65
	s_nop 1
	v_readfirstlane_b32 s10, v74
	v_readfirstlane_b32 s11, v75
	v_readfirstlane_b32 s98, v66
	v_readfirstlane_b32 s99, v67
	v_readfirstlane_b32 s100, v100
	s_nop 1
	s_sub_u32 s10, s10, 0x80
	s_subb_u32 s11, s11, 0
	s_sub_u32 s98, s98, 0x80
	s_subb_u32 s99, s99, 0
	v_subrev_u32_e32 v74, s10, v74
	v_subrev_u32_e32 v76, s10, v76
	v_subrev_u32_e32 v78, s10, v78
	v_subrev_u32_e32 v80, s10, v80
	v_subrev_u32_e32 v66, s98, v66
	v_subrev_u32_e32 v68, s98, v68
	v_subrev_u32_e32 v70, s98, v70
	v_subrev_u32_e32 v72, s98, v72
	s_add_u32 s10, s10, 0x80
	s_addc_u32 s11, s11, 0x0
	s_add_u32 s98, s98, 0x80
	s_addc_u32 s99, s99, 0x0
	s_branch .LBB0_156
.LBB0_155:
	ds_read_b128 v[82:85], v115 offset:32768
	ds_read_b128 v[86:89], v115 offset:34816
	ds_read_b128 v[90:93], v115 offset:36864
	ds_read_b128 v[94:97], v115 offset:38912
	ds_read_b128 v[120:123], v116 offset:49152
	ds_read_b128 v[124:127], v116 offset:51200
	ds_read_b128 v[128:131], v116 offset:53248
	ds_read_b128 v[132:135], v116 offset:55296
	ds_read_b128 v[136:139], v117 offset:32768
	ds_read_b128 v[140:143], v117 offset:34816
	ds_read_b128 v[144:147], v117 offset:36864
	ds_read_b128 v[148:151], v117 offset:38912
	ds_read_b128 v[152:155], v118 offset:49152
	ds_read_b128 v[156:159], v118 offset:51200
	ds_read_b128 v[160:163], v118 offset:53248
	ds_read_b128 v[164:167], v118 offset:55296
	s_add_i32 s7, s7, 2
	s_waitcnt lgkmcnt(0)
	v_mfma_f32_16x16x32_f16 v[0:3], v[120:123], v[82:85], v[0:3]
	v_mfma_f32_16x16x32_f16 v[4:7], v[124:127], v[82:85], v[4:7]
	v_mfma_f32_16x16x32_f16 v[8:11], v[128:131], v[82:85], v[8:11]
	v_mfma_f32_16x16x32_f16 v[12:15], v[132:135], v[82:85], v[12:15]
	v_mfma_f32_16x16x32_f16 v[16:19], v[120:123], v[86:89], v[16:19]
	v_mfma_f32_16x16x32_f16 v[20:23], v[124:127], v[86:89], v[20:23]
	v_mfma_f32_16x16x32_f16 v[24:27], v[128:131], v[86:89], v[24:27]
	v_mfma_f32_16x16x32_f16 v[28:31], v[132:135], v[86:89], v[28:31]
	v_mfma_f32_16x16x32_f16 v[82:85], v[120:123], v[90:93], v[32:35]
	v_mfma_f32_16x16x32_f16 v[86:89], v[124:127], v[90:93], v[36:39]
	v_mfma_f32_16x16x32_f16 v[168:171], v[128:131], v[90:93], v[40:43]
	v_mfma_f32_16x16x32_f16 v[90:93], v[132:135], v[90:93], v[44:47]
	v_mfma_f32_16x16x32_f16 v[120:123], v[120:123], v[94:97], v[48:51]
	v_mfma_f32_16x16x32_f16 v[124:127], v[124:127], v[94:97], v[52:55]
	v_mfma_f32_16x16x32_f16 v[128:131], v[128:131], v[94:97], v[56:59]
	v_mfma_f32_16x16x32_f16 v[94:97], v[132:135], v[94:97], v[60:63]
	v_mfma_f32_16x16x32_f16 v[60:63], v[152:155], v[136:139], v[0:3]
	v_mfma_f32_16x16x32_f16 v[56:59], v[156:159], v[136:139], v[4:7]
	v_mfma_f32_16x16x32_f16 v[52:55], v[160:163], v[136:139], v[8:11]
	v_mfma_f32_16x16x32_f16 v[48:51], v[164:167], v[136:139], v[12:15]
	v_mfma_f32_16x16x32_f16 v[44:47], v[152:155], v[140:143], v[16:19]
	v_mfma_f32_16x16x32_f16 v[40:43], v[156:159], v[140:143], v[20:23]
	v_mfma_f32_16x16x32_f16 v[36:39], v[160:163], v[140:143], v[24:27]
	v_mfma_f32_16x16x32_f16 v[32:35], v[164:167], v[140:143], v[28:31]
	v_mfma_f32_16x16x32_f16 v[28:31], v[152:155], v[144:147], v[82:85]
	v_mfma_f32_16x16x32_f16 v[24:27], v[156:159], v[144:147], v[86:89]
	v_mfma_f32_16x16x32_f16 v[20:23], v[160:163], v[144:147], v[168:171]
	v_mfma_f32_16x16x32_f16 v[16:19], v[164:167], v[144:147], v[90:93]
	v_mfma_f32_16x16x32_f16 v[12:15], v[152:155], v[148:151], v[120:123]
	v_mfma_f32_16x16x32_f16 v[8:11], v[156:159], v[148:151], v[124:127]
	v_mfma_f32_16x16x32_f16 v[4:7], v[160:163], v[148:151], v[128:131]
	v_mfma_f32_16x16x32_f16 v[0:3], v[164:167], v[148:151], v[94:97]
	s_andn2_b64 vcc, exec, s[12:13]
	s_cbranch_vccz .LBB0_153
.LBB0_156:
	s_waitcnt vmcnt(0)
	s_waitcnt vmcnt(0) lgkmcnt(0)
	s_barrier
	s_add_i32 m0, s100, 0x8000
	s_nop 0
	global_load_lds_dwordx4 v74, s[10:11]
	s_add_i32 m0, s100, 0x9000
	s_nop 0
	global_load_lds_dwordx4 v76, s[10:11]
	s_add_i32 m0, s100, 0xa000
	s_nop 0
	global_load_lds_dwordx4 v78, s[10:11]
	s_add_i32 m0, s100, 0xb000
	s_nop 0
	global_load_lds_dwordx4 v80, s[10:11]
	s_add_i32 m0, s100, 0xc000
	s_nop 0
	global_load_lds_dwordx4 v66, s[98:99]
	s_add_i32 m0, s100, 0xd000
	s_nop 0
	global_load_lds_dwordx4 v68, s[98:99]
	s_add_i32 m0, s100, 0xe000
	s_nop 0
	global_load_lds_dwordx4 v70, s[98:99]
	s_add_i32 m0, s100, 0xf000
	s_nop 0
	global_load_lds_dwordx4 v72, s[98:99]
	s_add_u32 s10, s10, 0x80
	s_addc_u32 s11, s11, 0
	s_add_u32 s98, s98, 0x80
	s_addc_u32 s99, s99, 0
	ds_read_b128 v[120:123], v115
	ds_read_b128 v[124:127], v115 offset:2048
	ds_read_b128 v[128:131], v115 offset:4096
	ds_read_b128 v[132:135], v115 offset:6144
	ds_read_b128 v[136:139], v116 offset:16384
	ds_read_b128 v[140:143], v116 offset:18432
	ds_read_b128 v[144:147], v116 offset:20480
	ds_read_b128 v[148:151], v116 offset:22528
	ds_read_b128 v[152:155], v117
	ds_read_b128 v[156:159], v117 offset:2048
	ds_read_b128 v[160:163], v117 offset:4096
	ds_read_b128 v[164:167], v117 offset:6144
	ds_read_b128 v[168:171], v118 offset:16384
	ds_read_b128 v[176:179], v118 offset:18432
	ds_read_b128 v[180:183], v118 offset:20480
	ds_read_b128 v[184:187], v118 offset:22528
	s_waitcnt lgkmcnt(0)
	v_mfma_f32_16x16x32_f16 v[60:63], v[136:139], v[120:123], v[60:63]
	v_mfma_f32_16x16x32_f16 v[56:59], v[140:143], v[120:123], v[56:59]
	v_mfma_f32_16x16x32_f16 v[52:55], v[144:147], v[120:123], v[52:55]
	v_mfma_f32_16x16x32_f16 v[48:51], v[148:151], v[120:123], v[48:51]
	v_mfma_f32_16x16x32_f16 v[44:47], v[136:139], v[124:127], v[44:47]
	v_mfma_f32_16x16x32_f16 v[40:43], v[140:143], v[124:127], v[40:43]
	v_mfma_f32_16x16x32_f16 v[36:39], v[144:147], v[124:127], v[36:39]
	v_mfma_f32_16x16x32_f16 v[32:35], v[148:151], v[124:127], v[32:35]
	v_mfma_f32_16x16x32_f16 v[120:123], v[136:139], v[128:131], v[28:31]
	v_mfma_f32_16x16x32_f16 v[124:127], v[140:143], v[128:131], v[24:27]
	v_mfma_f32_16x16x32_f16 v[188:191], v[144:147], v[128:131], v[20:23]
	v_mfma_f32_16x16x32_f16 v[128:131], v[148:151], v[128:131], v[16:19]
	v_mfma_f32_16x16x32_f16 v[136:139], v[136:139], v[132:135], v[12:15]
	v_mfma_f32_16x16x32_f16 v[140:143], v[140:143], v[132:135], v[8:11]
	v_mfma_f32_16x16x32_f16 v[144:147], v[144:147], v[132:135], v[4:7]
	v_mfma_f32_16x16x32_f16 v[132:135], v[148:151], v[132:135], v[0:3]
	v_mfma_f32_16x16x32_f16 v[0:3], v[168:171], v[152:155], v[60:63]
	v_mfma_f32_16x16x32_f16 v[4:7], v[176:179], v[152:155], v[56:59]
	v_mfma_f32_16x16x32_f16 v[8:11], v[180:183], v[152:155], v[52:55]
	v_mfma_f32_16x16x32_f16 v[12:15], v[184:187], v[152:155], v[48:51]
	v_mfma_f32_16x16x32_f16 v[16:19], v[168:171], v[156:159], v[44:47]
	v_mfma_f32_16x16x32_f16 v[20:23], v[176:179], v[156:159], v[40:43]
	v_mfma_f32_16x16x32_f16 v[24:27], v[180:183], v[156:159], v[36:39]
	v_mfma_f32_16x16x32_f16 v[28:31], v[184:187], v[156:159], v[32:35]
	v_mfma_f32_16x16x32_f16 v[32:35], v[168:171], v[160:163], v[120:123]
	v_mfma_f32_16x16x32_f16 v[36:39], v[176:179], v[160:163], v[124:127]
	v_mfma_f32_16x16x32_f16 v[40:43], v[180:183], v[160:163], v[188:191]
	v_mfma_f32_16x16x32_f16 v[44:47], v[184:187], v[160:163], v[128:131]
	v_mfma_f32_16x16x32_f16 v[48:51], v[168:171], v[164:167], v[136:139]
	v_mfma_f32_16x16x32_f16 v[52:55], v[176:179], v[164:167], v[140:143]
	v_mfma_f32_16x16x32_f16 v[56:59], v[180:183], v[164:167], v[144:147]
	v_mfma_f32_16x16x32_f16 v[60:63], v[184:187], v[164:167], v[132:135]
	s_waitcnt vmcnt(0)
	s_cmp_gt_u32 s7, 13
	s_cselect_b64 s[12:13], -1, 0
	s_and_b64 vcc, exec, s[12:13]
	s_waitcnt vmcnt(0)
	s_barrier
	s_cbranch_vccnz .LBB0_155
	s_mov_b32 m0, s100
	s_nop 0
	global_load_lds_dwordx4 v74, s[10:11]
	s_add_i32 m0, s100, 0x1000
	s_nop 0
	global_load_lds_dwordx4 v76, s[10:11]
	s_add_i32 m0, s100, 0x2000
	s_nop 0
	global_load_lds_dwordx4 v78, s[10:11]
	s_add_i32 m0, s100, 0x3000
	s_nop 0
	global_load_lds_dwordx4 v80, s[10:11]
	s_add_i32 m0, s100, 0x4000
	s_nop 0
	global_load_lds_dwordx4 v66, s[98:99]
	s_add_i32 m0, s100, 0x5000
	s_nop 0
	global_load_lds_dwordx4 v68, s[98:99]
	s_add_i32 m0, s100, 0x6000
	s_nop 0
	global_load_lds_dwordx4 v70, s[98:99]
	s_add_i32 m0, s100, 0x7000
	s_nop 0
	global_load_lds_dwordx4 v72, s[98:99]
	s_add_u32 s10, s10, 0x80
	s_addc_u32 s11, s11, 0
	s_add_u32 s98, s98, 0x80
	s_addc_u32 s99, s99, 0
	s_branch .LBB0_155

.LBB0_608:
	s_lshr_b32 s98, s3, 3
	s_and_b32 s99, s3, 7
	s_and_b32 s100, s88, 1
	s_lshl_b32 s98, s98, 1
	s_or_b32 s98, s98, s100
	s_lshr_b32 s100, s88, 1
	s_lshl_b32 s99, s99, 2
	s_or_b32 s99, s99, s100
	s_and_b32 s101, s98, 7
	s_lshr_b32 s98, s98, 3
	s_mul_i32 s99, s99, 17
	s_add_u32 s98, s98, s99
	s_lshl_b32 s99, s98, 3
	s_or_b32 s99, s99, s101
	s_mul_hi_i32 s10, s98, 0x78787879
	s_lshr_b32 s11, s10, 31
	s_ashr_i32 s10, s10, 3
	s_add_i32 s10, s10, s11
	s_mul_i32 s11, s10, 0xffffffef
	s_add_i32 s11, s11, s98
	s_lshl_b32 s11, s11, 3
	s_or_b32 s12, s11, s101
	v_mov_b32_e32 v0, v174
	s_ashr_i32 s13, s12, 31
	s_lshl_b64 s[34:35], s[12:13], 18
	v_bfe_u32 v2, v0, 1, 3
	v_lshrrev_b32_e32 v3, 4, v0
	v_bfe_u32 v4, v0, 4, 2
	v_lshlrev_b32_e32 v5, 7, v0
	v_and_b32_e32 v6, 0x780, v5
	v_bitop3_b32 v3, v3, v2, 3 bitop3:0x6c
	v_bitop3_b32 v2, v4, v2, 4 bitop3:0x36
	s_add_u32 s34, s38, s34
	v_lshl_or_b32 v7, v3, 4, v6
	v_lshl_or_b32 v6, v2, 4, v6
	v_lshlrev_b32_e32 v2, 6, v0
	s_addc_u32 s35, s39, s35
	s_ashr_i32 s11, s10, 31
	v_lshlrev_b32_e32 v1, 8, v0
	v_and_b32_e32 v8, 0xffffe000, v2
	v_lshlrev_b32_e32 v2, 4, v0
	s_lshl_b64 s[84:85], s[10:11], 18
	v_and_b32_e32 v1, 0xfffff800, v1
	v_xor_b32_e32 v0, v2, v0
	s_movk_i32 s11, 0x70
	v_add_u32_e32 v100, 0, v2
	v_and_or_b32 v64, v0, s11, v1
	v_readfirstlane_b32 s11, v100
	v_add_u32_e32 v101, 0x1000, v100
	s_mov_b32 m0, s11
	v_readfirstlane_b32 s11, v101
	v_add_u32_e32 v102, 0x2000, v100
	global_load_lds_dwordx4 v64, s[34:35]
	v_add_u32_e32 v0, 0x10000, v64
	s_mov_b32 m0, s11
	v_readfirstlane_b32 s11, v102
	v_add_u32_e32 v103, 0x3000, v100
	global_load_lds_dwordx4 v0, s[34:35]
	v_add_u32_e32 v2, 0x20000, v64
	s_mov_b32 m0, s11
	v_readfirstlane_b32 s11, v103
	v_add_u32_e32 v104, 0x4000, v100
	s_add_u32 s86, s90, s84
	global_load_lds_dwordx4 v2, s[34:35]
	v_add_u32_e32 v4, 0x30000, v64
	s_mov_b32 m0, s11
	v_readfirstlane_b32 s11, v104
	v_add_u32_e32 v105, 0x5000, v100
	s_addc_u32 s87, s91, s85
	global_load_lds_dwordx4 v4, s[34:35]
	s_mov_b32 m0, s11
	v_readfirstlane_b32 s11, v105
	v_add_u32_e32 v106, 0x6000, v100
	global_load_lds_dwordx4 v64, s[86:87]
	s_mov_b32 m0, s11
	v_readfirstlane_b32 s11, v106
	v_add_u32_e32 v107, 0x7000, v100
	global_load_lds_dwordx4 v0, s[86:87]
	s_mov_b32 m0, s11
	v_readfirstlane_b32 s11, v107
	global_load_lds_dwordx4 v2, s[86:87]
	s_mov_b32 m0, s11
	s_mul_i32 s11, s10, 0x88
	global_load_lds_dwordx4 v4, s[86:87]
	s_sub_i32 s34, s99, s11
	s_ashr_i32 s35, s34, 31
	s_lshl_b64 s[34:35], s[34:35], 18
	s_add_u32 s34, s38, s34
	v_and_b32_e32 v9, 0x2000, v5
	v_mov_b32_e32 v1, v65
	v_mov_b32_e32 v3, v65
	v_mov_b32_e32 v5, v65
	s_addc_u32 s35, s39, s35
	v_lshl_add_u64 v[66:67], s[34:35], 0, v[64:65]
	v_lshl_add_u64 v[68:69], s[34:35], 0, v[0:1]
	v_lshl_add_u64 v[70:71], s[34:35], 0, v[2:3]
	v_lshl_add_u64 v[72:73], s[34:35], 0, v[4:5]
	s_add_u32 s34, s36, s84
	v_add_u32_e32 v8, 0, v8
	v_add_u32_e32 v9, 0, v9
	s_addc_u32 s35, s37, s85
	v_lshl_add_u64 v[74:75], s[34:35], 0, v[64:65]
	v_lshl_add_u64 v[76:77], s[34:35], 0, v[0:1]
	v_lshl_add_u64 v[78:79], s[34:35], 0, v[2:3]
	v_lshl_add_u64 v[80:81], s[34:35], 0, v[4:5]
	s_mov_b64 s[84:85], 0
	v_add_u32_e32 v64, 0x8000, v100
	v_add_u32_e32 v108, 0x9000, v100
	v_add_u32_e32 v109, 0xa000, v100
	v_add_u32_e32 v110, 0xb000, v100
	v_add_u32_e32 v111, 0xc000, v100
	v_add_u32_e32 v112, 0xd000, v100
	v_add_u32_e32 v113, 0xe000, v100
	v_add_u32_e32 v114, 0xf000, v100
	v_add_u32_e32 v115, v8, v7
	v_add_u32_e32 v116, v9, v7
	v_add_u32_e32 v117, v8, v6
	v_add_u32_e32 v118, v9, v6
	s_mov_b32 s11, 0
	v_mov_b32_e32 v0, 0
	v_mov_b32_e32 v2, v65
	v_mov_b32_e32 v4, 0
	v_mov_b32_e32 v6, v65
	v_mov_b32_e32 v7, v65
	v_mov_b32_e32 v8, 0
	v_mov_b32_e32 v9, v65
	v_mov_b32_e32 v10, v65
	v_mov_b32_e32 v11, v65
	v_mov_b32_e32 v12, 0
	v_mov_b32_e32 v13, v65
	v_mov_b32_e32 v14, v65
	v_mov_b32_e32 v15, v65
	v_mov_b32_e32 v16, 0
	v_mov_b32_e32 v17, v65
	v_mov_b32_e32 v18, v65
	v_mov_b32_e32 v19, v65
	v_mov_b32_e32 v20, 0
	v_mov_b32_e32 v21, v65
	v_mov_b32_e32 v22, v65
	v_mov_b32_e32 v23, v65
	v_mov_b32_e32 v24, 0
	v_mov_b32_e32 v25, v65
	v_mov_b32_e32 v26, v65
	v_mov_b32_e32 v27, v65
	v_mov_b32_e32 v28, 0
	v_mov_b32_e32 v29, v65
	v_mov_b32_e32 v30, v65
	v_mov_b32_e32 v31, v65
	v_mov_b32_e32 v32, 0
	v_mov_b32_e32 v33, v65
	v_mov_b32_e32 v34, v65
	v_mov_b32_e32 v35, v65
	v_mov_b32_e32 v36, 0
	v_mov_b32_e32 v37, v65
	v_mov_b32_e32 v38, v65
	v_mov_b32_e32 v39, v65
	v_mov_b32_e32 v40, 0
	v_mov_b32_e32 v41, v65
	v_mov_b32_e32 v42, v65
	v_mov_b32_e32 v43, v65
	v_mov_b32_e32 v44, 0
	v_mov_b32_e32 v45, v65
	v_mov_b32_e32 v46, v65
	v_mov_b32_e32 v47, v65
	v_mov_b32_e32 v48, 0
	v_mov_b32_e32 v49, v65
	v_mov_b32_e32 v50, v65
	v_mov_b32_e32 v51, v65
	v_mov_b32_e32 v52, 0
	v_mov_b32_e32 v53, v65
	v_mov_b32_e32 v54, v65
	v_mov_b32_e32 v55, v65
	v_mov_b32_e32 v56, 0
	v_mov_b32_e32 v57, v65
	v_mov_b32_e32 v58, v65
	v_mov_b32_e32 v59, v65
	v_mov_b32_e32 v60, 0
	v_mov_b32_e32 v61, v65
	v_mov_b32_e32 v62, v65
	v_mov_b32_e32 v63, v65
	s_nop 1
	v_readfirstlane_b32 s84, v66
	v_readfirstlane_b32 s85, v67
	v_readfirstlane_b32 s98, v74
	v_readfirstlane_b32 s99, v75
	v_readfirstlane_b32 s100, v100
	s_nop 1
	s_sub_u32 s84, s84, 0x80
	s_subb_u32 s85, s85, 0
	s_sub_u32 s98, s98, 0x80
	s_subb_u32 s99, s99, 0
	v_subrev_u32_e32 v66, s84, v66
	v_subrev_u32_e32 v68, s84, v68
	v_subrev_u32_e32 v70, s84, v70
	v_subrev_u32_e32 v72, s84, v72
	v_subrev_u32_e32 v74, s98, v74
	v_subrev_u32_e32 v76, s98, v76
	v_subrev_u32_e32 v78, s98, v78
	v_subrev_u32_e32 v80, s98, v80
	s_add_u32 s84, s84, 0x80
	s_addc_u32 s85, s85, 0x0
	s_add_u32 s98, s98, 0x7c0080
	s_addc_u32 s99, s99, 0x0
	s_branch .LBB0_610
.LBB0_609:
	ds_read_b128 v[82:85], v115 offset:32768
	ds_read_b128 v[86:89], v115 offset:34816
	ds_read_b128 v[90:93], v115 offset:36864
	ds_read_b128 v[94:97], v115 offset:38912
	ds_read_b128 v[120:123], v116 offset:49152
	ds_read_b128 v[124:127], v116 offset:51200
	ds_read_b128 v[128:131], v116 offset:53248
	ds_read_b128 v[132:135], v116 offset:55296
	ds_read_b128 v[136:139], v117 offset:32768
	ds_read_b128 v[140:143], v117 offset:34816
	ds_read_b128 v[144:147], v117 offset:36864
	ds_read_b128 v[148:151], v117 offset:38912
	ds_read_b128 v[152:155], v118 offset:49152
	ds_read_b128 v[156:159], v118 offset:51200
	ds_read_b128 v[160:163], v118 offset:53248
	ds_read_b128 v[164:167], v118 offset:55296
	s_add_i32 s11, s11, 2
	s_waitcnt lgkmcnt(0)
	v_mfma_f32_16x16x32_f16 v[0:3], v[120:123], v[82:85], v[0:3]
	v_mfma_f32_16x16x32_f16 v[4:7], v[124:127], v[82:85], v[4:7]
	v_mfma_f32_16x16x32_f16 v[8:11], v[128:131], v[82:85], v[8:11]
	v_mfma_f32_16x16x32_f16 v[12:15], v[132:135], v[82:85], v[12:15]
	v_mfma_f32_16x16x32_f16 v[16:19], v[120:123], v[86:89], v[16:19]
	v_mfma_f32_16x16x32_f16 v[20:23], v[124:127], v[86:89], v[20:23]
	v_mfma_f32_16x16x32_f16 v[24:27], v[128:131], v[86:89], v[24:27]
	v_mfma_f32_16x16x32_f16 v[28:31], v[132:135], v[86:89], v[28:31]
	v_mfma_f32_16x16x32_f16 v[82:85], v[120:123], v[90:93], v[32:35]
	v_mfma_f32_16x16x32_f16 v[86:89], v[124:127], v[90:93], v[36:39]
	v_mfma_f32_16x16x32_f16 v[168:171], v[128:131], v[90:93], v[40:43]
	v_mfma_f32_16x16x32_f16 v[90:93], v[132:135], v[90:93], v[44:47]
	v_mfma_f32_16x16x32_f16 v[120:123], v[120:123], v[94:97], v[48:51]
	v_mfma_f32_16x16x32_f16 v[124:127], v[124:127], v[94:97], v[52:55]
	v_mfma_f32_16x16x32_f16 v[128:131], v[128:131], v[94:97], v[56:59]
	v_mfma_f32_16x16x32_f16 v[94:97], v[132:135], v[94:97], v[60:63]
	v_mfma_f32_16x16x32_f16 v[60:63], v[152:155], v[136:139], v[0:3]
	v_mfma_f32_16x16x32_f16 v[56:59], v[156:159], v[136:139], v[4:7]
	v_mfma_f32_16x16x32_f16 v[52:55], v[160:163], v[136:139], v[8:11]
	v_mfma_f32_16x16x32_f16 v[48:51], v[164:167], v[136:139], v[12:15]
	v_mfma_f32_16x16x32_f16 v[44:47], v[152:155], v[140:143], v[16:19]
	v_mfma_f32_16x16x32_f16 v[40:43], v[156:159], v[140:143], v[20:23]
	v_mfma_f32_16x16x32_f16 v[36:39], v[160:163], v[140:143], v[24:27]
	v_mfma_f32_16x16x32_f16 v[32:35], v[164:167], v[140:143], v[28:31]
	v_mfma_f32_16x16x32_f16 v[28:31], v[152:155], v[144:147], v[82:85]
	v_mfma_f32_16x16x32_f16 v[24:27], v[156:159], v[144:147], v[86:89]
	v_mfma_f32_16x16x32_f16 v[20:23], v[160:163], v[144:147], v[168:171]
	v_mfma_f32_16x16x32_f16 v[16:19], v[164:167], v[144:147], v[90:93]
	v_mfma_f32_16x16x32_f16 v[12:15], v[152:155], v[148:151], v[120:123]
	v_mfma_f32_16x16x32_f16 v[8:11], v[156:159], v[148:151], v[124:127]
	v_mfma_f32_16x16x32_f16 v[4:7], v[160:163], v[148:151], v[128:131]
	v_mfma_f32_16x16x32_f16 v[0:3], v[164:167], v[148:151], v[94:97]
	s_andn2_b64 vcc, exec, s[86:87]
	s_cbranch_vccz .LBB0_607
.LBB0_610:
	s_waitcnt vmcnt(0)
	s_waitcnt vmcnt(0) lgkmcnt(0)
	s_barrier
	s_add_i32 m0, s100, 0x8000
	s_nop 0
	global_load_lds_dwordx4 v66, s[84:85]
	s_add_i32 m0, s100, 0x9000
	s_nop 0
	global_load_lds_dwordx4 v68, s[84:85]
	s_add_i32 m0, s100, 0xa000
	s_nop 0
	global_load_lds_dwordx4 v70, s[84:85]
	s_add_i32 m0, s100, 0xb000
	s_nop 0
	global_load_lds_dwordx4 v72, s[84:85]
	s_add_i32 m0, s100, 0xc000
	s_nop 0
	global_load_lds_dwordx4 v74, s[98:99]
	s_add_i32 m0, s100, 0xd000
	s_nop 0
	global_load_lds_dwordx4 v76, s[98:99]
	s_add_i32 m0, s100, 0xe000
	s_nop 0
	global_load_lds_dwordx4 v78, s[98:99]
	s_add_i32 m0, s100, 0xf000
	s_nop 0
	global_load_lds_dwordx4 v80, s[98:99]
	s_add_u32 s84, s84, 0x80
	s_addc_u32 s85, s85, 0
	s_add_u32 s98, s98, 0x80
	s_addc_u32 s99, s99, 0
	ds_read_b128 v[120:123], v115
	ds_read_b128 v[124:127], v115 offset:2048
	ds_read_b128 v[128:131], v115 offset:4096
	ds_read_b128 v[132:135], v115 offset:6144
	ds_read_b128 v[136:139], v116 offset:16384
	ds_read_b128 v[140:143], v116 offset:18432
	ds_read_b128 v[144:147], v116 offset:20480
	ds_read_b128 v[148:151], v116 offset:22528
	ds_read_b128 v[152:155], v117
	ds_read_b128 v[156:159], v117 offset:2048
	ds_read_b128 v[160:163], v117 offset:4096
	ds_read_b128 v[164:167], v117 offset:6144
	ds_read_b128 v[168:171], v118 offset:16384
	ds_read_b128 v[176:179], v118 offset:18432
	ds_read_b128 v[180:183], v118 offset:20480
	ds_read_b128 v[184:187], v118 offset:22528
	s_waitcnt lgkmcnt(0)
	v_mfma_f32_16x16x32_f16 v[60:63], v[136:139], v[120:123], v[60:63]
	v_mfma_f32_16x16x32_f16 v[56:59], v[140:143], v[120:123], v[56:59]
	v_mfma_f32_16x16x32_f16 v[52:55], v[144:147], v[120:123], v[52:55]
	v_mfma_f32_16x16x32_f16 v[48:51], v[148:151], v[120:123], v[48:51]
	v_mfma_f32_16x16x32_f16 v[44:47], v[136:139], v[124:127], v[44:47]
	v_mfma_f32_16x16x32_f16 v[40:43], v[140:143], v[124:127], v[40:43]
	v_mfma_f32_16x16x32_f16 v[36:39], v[144:147], v[124:127], v[36:39]
	v_mfma_f32_16x16x32_f16 v[32:35], v[148:151], v[124:127], v[32:35]
	v_mfma_f32_16x16x32_f16 v[120:123], v[136:139], v[128:131], v[28:31]
	v_mfma_f32_16x16x32_f16 v[124:127], v[140:143], v[128:131], v[24:27]
	v_mfma_f32_16x16x32_f16 v[188:191], v[144:147], v[128:131], v[20:23]
	v_mfma_f32_16x16x32_f16 v[128:131], v[148:151], v[128:131], v[16:19]
	v_mfma_f32_16x16x32_f16 v[136:139], v[136:139], v[132:135], v[12:15]
	v_mfma_f32_16x16x32_f16 v[140:143], v[140:143], v[132:135], v[8:11]
	v_mfma_f32_16x16x32_f16 v[144:147], v[144:147], v[132:135], v[4:7]
	v_mfma_f32_16x16x32_f16 v[132:135], v[148:151], v[132:135], v[0:3]
	v_mfma_f32_16x16x32_f16 v[0:3], v[168:171], v[152:155], v[60:63]
	v_mfma_f32_16x16x32_f16 v[4:7], v[176:179], v[152:155], v[56:59]
	v_mfma_f32_16x16x32_f16 v[8:11], v[180:183], v[152:155], v[52:55]
	v_mfma_f32_16x16x32_f16 v[12:15], v[184:187], v[152:155], v[48:51]
	v_mfma_f32_16x16x32_f16 v[16:19], v[168:171], v[156:159], v[44:47]
	v_mfma_f32_16x16x32_f16 v[20:23], v[176:179], v[156:159], v[40:43]
	v_mfma_f32_16x16x32_f16 v[24:27], v[180:183], v[156:159], v[36:39]
	v_mfma_f32_16x16x32_f16 v[28:31], v[184:187], v[156:159], v[32:35]
	v_mfma_f32_16x16x32_f16 v[32:35], v[168:171], v[160:163], v[120:123]
	v_mfma_f32_16x16x32_f16 v[36:39], v[176:179], v[160:163], v[124:127]
	v_mfma_f32_16x16x32_f16 v[40:43], v[180:183], v[160:163], v[188:191]
	v_mfma_f32_16x16x32_f16 v[44:47], v[184:187], v[160:163], v[128:131]
	v_mfma_f32_16x16x32_f16 v[48:51], v[168:171], v[164:167], v[136:139]
	v_mfma_f32_16x16x32_f16 v[52:55], v[176:179], v[164:167], v[140:143]
	v_mfma_f32_16x16x32_f16 v[56:59], v[180:183], v[164:167], v[144:147]
	v_mfma_f32_16x16x32_f16 v[60:63], v[184:187], v[164:167], v[132:135]
	s_waitcnt vmcnt(0)
	s_cmp_gt_u32 s11, 13
	s_cselect_b64 s[86:87], -1, 0
	s_and_b64 vcc, exec, s[86:87]
	s_waitcnt vmcnt(0)
	s_barrier
	s_cbranch_vccnz .LBB0_609
	s_mov_b32 m0, s100
	s_nop 0
	global_load_lds_dwordx4 v66, s[84:85]
	s_add_i32 m0, s100, 0x1000
	s_nop 0
	global_load_lds_dwordx4 v68, s[84:85]
	s_add_i32 m0, s100, 0x2000
	s_nop 0
	global_load_lds_dwordx4 v70, s[84:85]
	s_add_i32 m0, s100, 0x3000
	s_nop 0
	global_load_lds_dwordx4 v72, s[84:85]
	s_add_i32 m0, s100, 0x4000
	s_nop 0
	global_load_lds_dwordx4 v74, s[98:99]
	s_add_i32 m0, s100, 0x5000
	s_nop 0
	global_load_lds_dwordx4 v76, s[98:99]
	s_add_i32 m0, s100, 0x6000
	s_nop 0
	global_load_lds_dwordx4 v78, s[98:99]
	s_add_i32 m0, s100, 0x7000
	s_nop 0
	global_load_lds_dwordx4 v80, s[98:99]
	s_add_u32 s84, s84, 0x80
	s_addc_u32 s85, s85, 0
	s_add_u32 s98, s98, 0x80
	s_addc_u32 s99, s99, 0
	s_branch .LBB0_609

.Lto_j_b1:
	s_mul_i32 s98, s98, 17
	s_add_u32 s98, s98, s99
	s_lshl_b32 s99, s98, 3
	s_or_b32 s99, s99, s90
	s_mul_hi_i32 s10, s98, 0x78787879
	s_lshr_b32 s11, s10, 31
	s_ashr_i32 s10, s10, 3
	s_add_i32 s10, s10, s11
	s_mul_i32 s11, s10, 0xffffffef
	s_add_i32 s11, s11, s98
	s_lshl_b32 s11, s11, 3
	s_or_b32 s12, s11, s90
	v_mov_b32_e32 v0, v174
	s_ashr_i32 s13, s12, 31
	s_lshl_b64 s[34:35], s[12:13], 18
	v_bfe_u32 v2, v0, 1, 3
	v_lshrrev_b32_e32 v3, 4, v0
	s_waitcnt vmcnt(5)
	v_bfe_u32 v4, v0, 4, 2
	v_lshlrev_b32_e32 v5, 7, v0
	v_and_b32_e32 v6, 0x780, v5
	v_bitop3_b32 v3, v3, v2, 3 bitop3:0x6c
	v_bitop3_b32 v2, v4, v2, 4 bitop3:0x36
	s_add_u32 s34, s38, s34
	v_lshl_or_b32 v7, v3, 4, v6
	v_lshl_or_b32 v6, v2, 4, v6
	v_lshlrev_b32_e32 v2, 6, v0
	s_addc_u32 s35, s39, s35
	s_ashr_i32 s11, s10, 31
	v_lshlrev_b32_e32 v1, 8, v0
	v_and_b32_e32 v8, 0xffffe000, v2
	v_lshlrev_b32_e32 v2, 4, v0
	s_lshl_b64 s[84:85], s[10:11], 18
	v_and_b32_e32 v1, 0xfffff800, v1
	v_xor_b32_e32 v0, v2, v0
	s_movk_i32 s11, 0x70
	v_add_u32_e32 v100, 0, v2
	v_and_or_b32 v64, v0, s11, v1
	v_readfirstlane_b32 s11, v100
	v_add_u32_e32 v101, 0x1000, v100
	s_mov_b32 m0, s11
	v_readfirstlane_b32 s11, v101
	v_add_u32_e32 v102, 0x2000, v100
	global_load_lds_dwordx4 v64, s[34:35]
	v_add_u32_e32 v0, 0x10000, v64
	s_mov_b32 m0, s11
	v_readfirstlane_b32 s11, v102
	v_add_u32_e32 v103, 0x3000, v100
	global_load_lds_dwordx4 v0, s[34:35]
	v_add_u32_e32 v2, 0x20000, v64
	s_mov_b32 m0, s11
	v_readfirstlane_b32 s11, v103
	v_add_u32_e32 v104, 0x4000, v100
	s_add_u32 s88, s70, s84
	global_load_lds_dwordx4 v2, s[34:35]
	v_add_u32_e32 v4, 0x30000, v64
	s_mov_b32 m0, s11
	v_readfirstlane_b32 s11, v104
	v_add_u32_e32 v105, 0x5000, v100
	s_addc_u32 s89, s71, s85
	global_load_lds_dwordx4 v4, s[34:35]
	s_mov_b32 m0, s11
	v_readfirstlane_b32 s11, v105
	v_add_u32_e32 v106, 0x6000, v100
	global_load_lds_dwordx4 v64, s[88:89]
	s_mov_b32 m0, s11
	v_readfirstlane_b32 s11, v106
	v_add_u32_e32 v107, 0x7000, v100
	global_load_lds_dwordx4 v0, s[88:89]
	s_mov_b32 m0, s11
	v_readfirstlane_b32 s11, v107
	global_load_lds_dwordx4 v2, s[88:89]
	s_mov_b32 m0, s11
	s_mul_i32 s11, s10, 0x88
	global_load_lds_dwordx4 v4, s[88:89]
	s_sub_i32 s34, s99, s11
	s_ashr_i32 s35, s34, 31
	s_lshl_b64 s[34:35], s[34:35], 18
	s_add_u32 s34, s38, s34
	v_and_b32_e32 v9, 0x2000, v5
	v_mov_b32_e32 v1, v65
	v_mov_b32_e32 v3, v65
	v_mov_b32_e32 v5, v65
	s_addc_u32 s35, s39, s35
	v_lshl_add_u64 v[66:67], s[34:35], 0, v[64:65]
	v_lshl_add_u64 v[68:69], s[34:35], 0, v[0:1]
	v_lshl_add_u64 v[70:71], s[34:35], 0, v[2:3]
	v_lshl_add_u64 v[72:73], s[34:35], 0, v[4:5]
	s_add_u32 s34, s36, s84
	v_add_u32_e32 v8, 0, v8
	v_add_u32_e32 v9, 0, v9
	s_addc_u32 s35, s37, s85
	v_lshl_add_u64 v[74:75], s[34:35], 0, v[64:65]
	v_lshl_add_u64 v[76:77], s[34:35], 0, v[0:1]
	v_lshl_add_u64 v[78:79], s[34:35], 0, v[2:3]
	v_lshl_add_u64 v[80:81], s[34:35], 0, v[4:5]
	s_mov_b64 s[84:85], 0
	v_add_u32_e32 v64, 0x8000, v100
	v_add_u32_e32 v108, 0x9000, v100
	v_add_u32_e32 v109, 0xa000, v100
	v_add_u32_e32 v110, 0xb000, v100
	v_add_u32_e32 v111, 0xc000, v100
	v_add_u32_e32 v112, 0xd000, v100
	v_add_u32_e32 v113, 0xe000, v100
	v_add_u32_e32 v114, 0xf000, v100
	v_add_u32_e32 v115, v8, v7
	v_add_u32_e32 v116, v9, v7
	v_add_u32_e32 v117, v8, v6
	v_add_u32_e32 v118, v9, v6
	s_mov_b32 s11, 0
	v_mov_b32_e32 v0, 0
	v_mov_b32_e32 v2, v65
	v_mov_b32_e32 v4, 0
	v_mov_b32_e32 v6, v65
	v_mov_b32_e32 v7, v65
	v_mov_b32_e32 v8, 0
	v_mov_b32_e32 v9, v65
	v_mov_b32_e32 v10, v65
	v_mov_b32_e32 v11, v65
	v_mov_b32_e32 v12, 0
	v_mov_b32_e32 v13, v65
	v_mov_b32_e32 v14, v65
	v_mov_b32_e32 v15, v65
	v_mov_b32_e32 v16, 0
	v_mov_b32_e32 v17, v65
	v_mov_b32_e32 v18, v65
	v_mov_b32_e32 v19, v65
	v_mov_b32_e32 v20, 0
	v_mov_b32_e32 v21, v65
	v_mov_b32_e32 v22, v65
	v_mov_b32_e32 v23, v65
	v_mov_b32_e32 v24, 0
	v_mov_b32_e32 v25, v65
	v_mov_b32_e32 v26, v65
	v_mov_b32_e32 v27, v65
	v_mov_b32_e32 v28, 0
	v_mov_b32_e32 v29, v65
	v_mov_b32_e32 v30, v65
	v_mov_b32_e32 v31, v65
	v_mov_b32_e32 v32, 0
	v_mov_b32_e32 v33, v65
	v_mov_b32_e32 v34, v65
	v_mov_b32_e32 v35, v65
	v_mov_b32_e32 v36, 0
	v_mov_b32_e32 v37, v65
	v_mov_b32_e32 v38, v65
	v_mov_b32_e32 v39, v65
	v_mov_b32_e32 v40, 0
	v_mov_b32_e32 v41, v65
	v_mov_b32_e32 v42, v65
	v_mov_b32_e32 v43, v65
	v_mov_b32_e32 v44, 0
	v_mov_b32_e32 v45, v65
	v_mov_b32_e32 v46, v65
	v_mov_b32_e32 v47, v65
	v_mov_b32_e32 v48, 0
	v_mov_b32_e32 v49, v65
	v_mov_b32_e32 v50, v65
	v_mov_b32_e32 v51, v65
	v_mov_b32_e32 v52, 0
	v_mov_b32_e32 v53, v65
	s_waitcnt vmcnt(0)
	v_mov_b32_e32 v54, v65
	v_mov_b32_e32 v55, v65
	v_mov_b32_e32 v56, 0
	v_mov_b32_e32 v57, v65
	v_mov_b32_e32 v58, v65
	v_mov_b32_e32 v59, v65
	v_mov_b32_e32 v60, 0
	v_mov_b32_e32 v61, v65
	v_mov_b32_e32 v62, v65
	v_mov_b32_e32 v63, v65
	s_nop 1
	v_readfirstlane_b32 s84, v66
	v_readfirstlane_b32 s85, v67
	v_readfirstlane_b32 s98, v74
	v_readfirstlane_b32 s99, v75
	v_readfirstlane_b32 s100, v100
	s_nop 1
	s_sub_u32 s84, s84, 0x80
	s_subb_u32 s85, s85, 0
	s_sub_u32 s98, s98, 0x80
	s_subb_u32 s99, s99, 0
	v_subrev_u32_e32 v66, s84, v66
	v_subrev_u32_e32 v68, s84, v68
	v_subrev_u32_e32 v70, s84, v70
	v_subrev_u32_e32 v72, s84, v72
	v_subrev_u32_e32 v74, s98, v74
	v_subrev_u32_e32 v76, s98, v76
	v_subrev_u32_e32 v78, s98, v78
	v_subrev_u32_e32 v80, s98, v80
	s_add_u32 s84, s84, 0x80
	s_addc_u32 s85, s85, 0x0
	s_add_u32 s98, s98, 0x11c0080
	s_addc_u32 s99, s99, 0x0
	s_branch .LBB0_752
.LBB0_751:
	ds_read_b128 v[82:85], v115 offset:32768
	ds_read_b128 v[86:89], v115 offset:34816
	ds_read_b128 v[90:93], v115 offset:36864
	ds_read_b128 v[94:97], v115 offset:38912
	ds_read_b128 v[120:123], v116 offset:49152
	ds_read_b128 v[124:127], v116 offset:51200
	ds_read_b128 v[128:131], v116 offset:53248
	ds_read_b128 v[132:135], v116 offset:55296
	ds_read_b128 v[136:139], v117 offset:32768
	ds_read_b128 v[140:143], v117 offset:34816
	ds_read_b128 v[144:147], v117 offset:36864
	ds_read_b128 v[148:151], v117 offset:38912
	ds_read_b128 v[152:155], v118 offset:49152
	ds_read_b128 v[156:159], v118 offset:51200
	ds_read_b128 v[160:163], v118 offset:53248
	ds_read_b128 v[164:167], v118 offset:55296
	s_add_i32 s11, s11, 2
	s_waitcnt lgkmcnt(0)
	v_mfma_f32_16x16x32_f16 v[0:3], v[120:123], v[82:85], v[0:3]
	v_mfma_f32_16x16x32_f16 v[4:7], v[124:127], v[82:85], v[4:7]
	v_mfma_f32_16x16x32_f16 v[8:11], v[128:131], v[82:85], v[8:11]
	v_mfma_f32_16x16x32_f16 v[12:15], v[132:135], v[82:85], v[12:15]
	v_mfma_f32_16x16x32_f16 v[16:19], v[120:123], v[86:89], v[16:19]
	v_mfma_f32_16x16x32_f16 v[20:23], v[124:127], v[86:89], v[20:23]
	v_mfma_f32_16x16x32_f16 v[24:27], v[128:131], v[86:89], v[24:27]
	v_mfma_f32_16x16x32_f16 v[28:31], v[132:135], v[86:89], v[28:31]
	v_mfma_f32_16x16x32_f16 v[82:85], v[120:123], v[90:93], v[32:35]
	v_mfma_f32_16x16x32_f16 v[86:89], v[124:127], v[90:93], v[36:39]
	v_mfma_f32_16x16x32_f16 v[168:171], v[128:131], v[90:93], v[40:43]
	v_mfma_f32_16x16x32_f16 v[90:93], v[132:135], v[90:93], v[44:47]
	v_mfma_f32_16x16x32_f16 v[120:123], v[120:123], v[94:97], v[48:51]
	v_mfma_f32_16x16x32_f16 v[124:127], v[124:127], v[94:97], v[52:55]
	v_mfma_f32_16x16x32_f16 v[128:131], v[128:131], v[94:97], v[56:59]
	v_mfma_f32_16x16x32_f16 v[94:97], v[132:135], v[94:97], v[60:63]
	v_mfma_f32_16x16x32_f16 v[60:63], v[152:155], v[136:139], v[0:3]
	v_mfma_f32_16x16x32_f16 v[56:59], v[156:159], v[136:139], v[4:7]
	v_mfma_f32_16x16x32_f16 v[52:55], v[160:163], v[136:139], v[8:11]
	v_mfma_f32_16x16x32_f16 v[48:51], v[164:167], v[136:139], v[12:15]
	v_mfma_f32_16x16x32_f16 v[44:47], v[152:155], v[140:143], v[16:19]
	v_mfma_f32_16x16x32_f16 v[40:43], v[156:159], v[140:143], v[20:23]
	v_mfma_f32_16x16x32_f16 v[36:39], v[160:163], v[140:143], v[24:27]
	v_mfma_f32_16x16x32_f16 v[32:35], v[164:167], v[140:143], v[28:31]
	v_mfma_f32_16x16x32_f16 v[28:31], v[152:155], v[144:147], v[82:85]
	v_mfma_f32_16x16x32_f16 v[24:27], v[156:159], v[144:147], v[86:89]
	v_mfma_f32_16x16x32_f16 v[20:23], v[160:163], v[144:147], v[168:171]
	v_mfma_f32_16x16x32_f16 v[16:19], v[164:167], v[144:147], v[90:93]
	v_mfma_f32_16x16x32_f16 v[12:15], v[152:155], v[148:151], v[120:123]
	v_mfma_f32_16x16x32_f16 v[8:11], v[156:159], v[148:151], v[124:127]
	v_mfma_f32_16x16x32_f16 v[4:7], v[160:163], v[148:151], v[128:131]
	v_mfma_f32_16x16x32_f16 v[0:3], v[164:167], v[148:151], v[94:97]
	s_andn2_b64 vcc, exec, s[88:89]
	s_cbranch_vccz .LBB0_749
.LBB0_752:
	s_waitcnt vmcnt(0)
	s_waitcnt lgkmcnt(0)
	s_barrier
	s_add_i32 m0, s100, 0x8000
	s_nop 0
	global_load_lds_dwordx4 v66, s[84:85]
	s_add_i32 m0, s100, 0x9000
	s_nop 0
	global_load_lds_dwordx4 v68, s[84:85]
	s_add_i32 m0, s100, 0xa000
	s_nop 0
	global_load_lds_dwordx4 v70, s[84:85]
	s_add_i32 m0, s100, 0xb000
	s_nop 0
	global_load_lds_dwordx4 v72, s[84:85]
	s_add_i32 m0, s100, 0xc000
	s_nop 0
	global_load_lds_dwordx4 v74, s[98:99]
	s_add_i32 m0, s100, 0xd000
	s_nop 0
	global_load_lds_dwordx4 v76, s[98:99]
	s_add_i32 m0, s100, 0xe000
	s_nop 0
	global_load_lds_dwordx4 v78, s[98:99]
	s_add_i32 m0, s100, 0xf000
	s_nop 0
	global_load_lds_dwordx4 v80, s[98:99]
	s_add_u32 s84, s84, 0x80
	s_addc_u32 s85, s85, 0
	s_add_u32 s98, s98, 0x80
	s_addc_u32 s99, s99, 0
	ds_read_b128 v[120:123], v115
	ds_read_b128 v[124:127], v115 offset:2048
	ds_read_b128 v[128:131], v115 offset:4096
	ds_read_b128 v[132:135], v115 offset:6144
	ds_read_b128 v[136:139], v116 offset:16384
	ds_read_b128 v[140:143], v116 offset:18432
	ds_read_b128 v[144:147], v116 offset:20480
	ds_read_b128 v[148:151], v116 offset:22528
	ds_read_b128 v[152:155], v117
	ds_read_b128 v[156:159], v117 offset:2048
	ds_read_b128 v[160:163], v117 offset:4096
	ds_read_b128 v[164:167], v117 offset:6144
	ds_read_b128 v[168:171], v118 offset:16384
	ds_read_b128 v[176:179], v118 offset:18432
	ds_read_b128 v[180:183], v118 offset:20480
	ds_read_b128 v[184:187], v118 offset:22528
	s_waitcnt lgkmcnt(0)
	v_mfma_f32_16x16x32_f16 v[60:63], v[136:139], v[120:123], v[60:63]
	v_mfma_f32_16x16x32_f16 v[56:59], v[140:143], v[120:123], v[56:59]
	v_mfma_f32_16x16x32_f16 v[52:55], v[144:147], v[120:123], v[52:55]
	v_mfma_f32_16x16x32_f16 v[48:51], v[148:151], v[120:123], v[48:51]
	v_mfma_f32_16x16x32_f16 v[44:47], v[136:139], v[124:127], v[44:47]
	v_mfma_f32_16x16x32_f16 v[40:43], v[140:143], v[124:127], v[40:43]
	v_mfma_f32_16x16x32_f16 v[36:39], v[144:147], v[124:127], v[36:39]
	v_mfma_f32_16x16x32_f16 v[32:35], v[148:151], v[124:127], v[32:35]
	v_mfma_f32_16x16x32_f16 v[120:123], v[136:139], v[128:131], v[28:31]
	v_mfma_f32_16x16x32_f16 v[124:127], v[140:143], v[128:131], v[24:27]
	v_mfma_f32_16x16x32_f16 v[188:191], v[144:147], v[128:131], v[20:23]
	v_mfma_f32_16x16x32_f16 v[128:131], v[148:151], v[128:131], v[16:19]
	v_mfma_f32_16x16x32_f16 v[136:139], v[136:139], v[132:135], v[12:15]
	v_mfma_f32_16x16x32_f16 v[140:143], v[140:143], v[132:135], v[8:11]
	v_mfma_f32_16x16x32_f16 v[144:147], v[144:147], v[132:135], v[4:7]
	v_mfma_f32_16x16x32_f16 v[132:135], v[148:151], v[132:135], v[0:3]
	v_mfma_f32_16x16x32_f16 v[0:3], v[168:171], v[152:155], v[60:63]
	v_mfma_f32_16x16x32_f16 v[4:7], v[176:179], v[152:155], v[56:59]
	v_mfma_f32_16x16x32_f16 v[8:11], v[180:183], v[152:155], v[52:55]
	v_mfma_f32_16x16x32_f16 v[12:15], v[184:187], v[152:155], v[48:51]
	v_mfma_f32_16x16x32_f16 v[16:19], v[168:171], v[156:159], v[44:47]
	v_mfma_f32_16x16x32_f16 v[20:23], v[176:179], v[156:159], v[40:43]
	v_mfma_f32_16x16x32_f16 v[24:27], v[180:183], v[156:159], v[36:39]
	v_mfma_f32_16x16x32_f16 v[28:31], v[184:187], v[156:159], v[32:35]
	v_mfma_f32_16x16x32_f16 v[32:35], v[168:171], v[160:163], v[120:123]
	v_mfma_f32_16x16x32_f16 v[36:39], v[176:179], v[160:163], v[124:127]
	v_mfma_f32_16x16x32_f16 v[40:43], v[180:183], v[160:163], v[188:191]
	v_mfma_f32_16x16x32_f16 v[44:47], v[184:187], v[160:163], v[128:131]
	v_mfma_f32_16x16x32_f16 v[48:51], v[168:171], v[164:167], v[136:139]
	v_mfma_f32_16x16x32_f16 v[52:55], v[176:179], v[164:167], v[140:143]
	v_mfma_f32_16x16x32_f16 v[56:59], v[180:183], v[164:167], v[144:147]
	v_mfma_f32_16x16x32_f16 v[60:63], v[184:187], v[164:167], v[132:135]
	s_waitcnt vmcnt(0)
	s_cmp_gt_u32 s11, 13
	s_cselect_b64 s[88:89], -1, 0
	s_and_b64 vcc, exec, s[88:89]
	s_waitcnt vmcnt(0)
	s_barrier
	s_cbranch_vccnz .LBB0_751
	s_mov_b32 m0, s100
	s_nop 0
	global_load_lds_dwordx4 v66, s[84:85]
	s_add_i32 m0, s100, 0x1000
	s_nop 0
	global_load_lds_dwordx4 v68, s[84:85]
	s_add_i32 m0, s100, 0x2000
	s_nop 0
	global_load_lds_dwordx4 v70, s[84:85]
	s_add_i32 m0, s100, 0x3000
	s_nop 0
	global_load_lds_dwordx4 v72, s[84:85]
	s_add_i32 m0, s100, 0x4000
	s_nop 0
	global_load_lds_dwordx4 v74, s[98:99]
	s_add_i32 m0, s100, 0x5000
	s_nop 0
	global_load_lds_dwordx4 v76, s[98:99]
	s_add_i32 m0, s100, 0x6000
	s_nop 0
	global_load_lds_dwordx4 v78, s[98:99]
	s_add_i32 m0, s100, 0x7000
	s_nop 0
	global_load_lds_dwordx4 v80, s[98:99]
	s_add_u32 s84, s84, 0x80
	s_addc_u32 s85, s85, 0
	s_add_u32 s98, s98, 0x80
	s_addc_u32 s99, s99, 0
	s_branch .LBB0_751

.LBB0_882:
	s_mul_hi_u32 s98, s3, 0xba2e8ba3
	s_lshr_b32 s98, s98, 3
	s_mul_i32 s99, s98, 11
	s_sub_u32 s99, s3, s99
	s_and_b32 s100, s90, 1
	s_lshl_b32 s98, s98, 1
	s_or_b32 s98, s98, s100
	s_lshr_b32 s100, s90, 1
	s_lshl_b32 s99, s99, 2
	s_or_b32 s99, s99, s100
	s_and_b32 s101, s98, 7
	s_lshr_b32 s98, s98, 3
	s_mul_i32 s99, s99, 17
	s_add_u32 s98, s98, s99
	s_lshl_b32 s99, s98, 3
	s_or_b32 s99, s99, s101
	s_mul_hi_i32 s10, s98, 0x78787879
	s_lshr_b32 s11, s10, 31
	s_ashr_i32 s10, s10, 3
	s_add_i32 s10, s10, s11
	s_mul_i32 s11, s10, 0xffffffef
	s_add_i32 s11, s11, s98
	s_lshl_b32 s11, s11, 3
	s_or_b32 s12, s11, s101
	v_mov_b32_e32 v0, v174
	s_ashr_i32 s13, s12, 31
	s_lshl_b64 s[34:35], s[12:13], 18
	v_bfe_u32 v2, v0, 1, 3
	v_lshrrev_b32_e32 v3, 4, v0
	v_bfe_u32 v4, v0, 4, 2
	v_lshlrev_b32_e32 v5, 7, v0
	v_and_b32_e32 v6, 0x780, v5
	v_bitop3_b32 v3, v3, v2, 3 bitop3:0x6c
	v_bitop3_b32 v2, v4, v2, 4 bitop3:0x36
	s_add_u32 s34, s38, s34
	v_lshl_or_b32 v7, v3, 4, v6
	v_lshl_or_b32 v6, v2, 4, v6
	v_lshlrev_b32_e32 v2, 6, v0
	s_addc_u32 s35, s39, s35
	s_ashr_i32 s11, s10, 31
	v_lshlrev_b32_e32 v1, 8, v0
	v_and_b32_e32 v8, 0xffffe000, v2
	v_lshlrev_b32_e32 v2, 4, v0
	s_lshl_b64 s[84:85], s[10:11], 18
	v_and_b32_e32 v1, 0xfffff800, v1
	v_xor_b32_e32 v0, v2, v0
	s_movk_i32 s11, 0x70
	v_add_u32_e32 v100, 0, v2
	v_and_or_b32 v64, v0, s11, v1
	v_readfirstlane_b32 s11, v100
	v_add_u32_e32 v101, 0x1000, v100
	s_mov_b32 m0, s11
	v_readfirstlane_b32 s11, v101
	v_add_u32_e32 v102, 0x2000, v100
	global_load_lds_dwordx4 v64, s[34:35]
	v_add_u32_e32 v0, 0x10000, v64
	s_mov_b32 m0, s11
	v_readfirstlane_b32 s11, v102
	v_add_u32_e32 v103, 0x3000, v100
	global_load_lds_dwordx4 v0, s[34:35]
	v_add_u32_e32 v2, 0x20000, v64
	s_mov_b32 m0, s11
	v_readfirstlane_b32 s11, v103
	v_add_u32_e32 v104, 0x4000, v100
	s_add_u32 s88, s92, s84
	global_load_lds_dwordx4 v2, s[34:35]
	v_add_u32_e32 v4, 0x30000, v64
	s_mov_b32 m0, s11
	v_readfirstlane_b32 s11, v104
	v_add_u32_e32 v105, 0x5000, v100
	s_addc_u32 s89, s93, s85
	global_load_lds_dwordx4 v4, s[34:35]
	s_mov_b32 m0, s11
	v_readfirstlane_b32 s11, v105
	v_add_u32_e32 v106, 0x6000, v100
	global_load_lds_dwordx4 v64, s[88:89]
	s_mov_b32 m0, s11
	v_readfirstlane_b32 s11, v106
	v_add_u32_e32 v107, 0x7000, v100
	global_load_lds_dwordx4 v0, s[88:89]
	s_mov_b32 m0, s11
	v_readfirstlane_b32 s11, v107
	global_load_lds_dwordx4 v2, s[88:89]
	s_mov_b32 m0, s11
	s_mul_i32 s11, s10, 0x88
	global_load_lds_dwordx4 v4, s[88:89]
	s_sub_i32 s34, s99, s11
	s_ashr_i32 s35, s34, 31
	s_lshl_b64 s[34:35], s[34:35], 18
	s_add_u32 s34, s38, s34
	v_and_b32_e32 v9, 0x2000, v5
	v_mov_b32_e32 v1, v65
	v_mov_b32_e32 v3, v65
	v_mov_b32_e32 v5, v65
	s_addc_u32 s35, s39, s35
	v_lshl_add_u64 v[66:67], s[34:35], 0, v[64:65]
	v_lshl_add_u64 v[68:69], s[34:35], 0, v[0:1]
	v_lshl_add_u64 v[70:71], s[34:35], 0, v[2:3]
	v_lshl_add_u64 v[72:73], s[34:35], 0, v[4:5]
	s_add_u32 s34, s36, s84
	v_add_u32_e32 v8, 0, v8
	v_add_u32_e32 v9, 0, v9
	s_addc_u32 s35, s37, s85
	v_lshl_add_u64 v[74:75], s[34:35], 0, v[64:65]
	v_lshl_add_u64 v[76:77], s[34:35], 0, v[0:1]
	v_lshl_add_u64 v[78:79], s[34:35], 0, v[2:3]
	v_lshl_add_u64 v[80:81], s[34:35], 0, v[4:5]
	s_mov_b64 s[84:85], 0
	v_add_u32_e32 v64, 0x8000, v100
	v_add_u32_e32 v108, 0x9000, v100
	v_add_u32_e32 v109, 0xa000, v100
	v_add_u32_e32 v110, 0xb000, v100
	v_add_u32_e32 v111, 0xc000, v100
	v_add_u32_e32 v112, 0xd000, v100
	v_add_u32_e32 v113, 0xe000, v100
	v_add_u32_e32 v114, 0xf000, v100
	v_add_u32_e32 v115, v8, v7
	v_add_u32_e32 v116, v9, v7
	v_add_u32_e32 v117, v8, v6
	v_add_u32_e32 v118, v9, v6
	s_mov_b32 s11, 0
	v_mov_b32_e32 v0, 0
	v_mov_b32_e32 v2, v65
	v_mov_b32_e32 v8, 0
	v_mov_b32_e32 v9, v65
	v_mov_b32_e32 v10, v65
	v_mov_b32_e32 v11, v65
	v_mov_b32_e32 v4, 0
	v_mov_b32_e32 v6, v65
	v_mov_b32_e32 v7, v65
	v_mov_b32_e32 v12, 0
	v_mov_b32_e32 v13, v65
	v_mov_b32_e32 v14, v65
	v_mov_b32_e32 v15, v65
	v_mov_b32_e32 v16, 0
	v_mov_b32_e32 v17, v65
	v_mov_b32_e32 v18, v65
	v_mov_b32_e32 v19, v65
	v_mov_b32_e32 v24, 0
	v_mov_b32_e32 v25, v65
	v_mov_b32_e32 v26, v65
	v_mov_b32_e32 v27, v65
	v_mov_b32_e32 v20, 0
	v_mov_b32_e32 v21, v65
	v_mov_b32_e32 v22, v65
	v_mov_b32_e32 v23, v65
	v_mov_b32_e32 v28, 0
	v_mov_b32_e32 v29, v65
	v_mov_b32_e32 v30, v65
	v_mov_b32_e32 v31, v65
	v_mov_b32_e32 v32, 0
	v_mov_b32_e32 v33, v65
	v_mov_b32_e32 v34, v65
	v_mov_b32_e32 v35, v65
	v_mov_b32_e32 v40, 0
	v_mov_b32_e32 v41, v65
	v_mov_b32_e32 v42, v65
	v_mov_b32_e32 v43, v65
	v_mov_b32_e32 v36, 0
	v_mov_b32_e32 v37, v65
	v_mov_b32_e32 v38, v65
	v_mov_b32_e32 v39, v65
	v_mov_b32_e32 v44, 0
	v_mov_b32_e32 v45, v65
	v_mov_b32_e32 v46, v65
	v_mov_b32_e32 v47, v65
	v_mov_b32_e32 v48, 0
	v_mov_b32_e32 v49, v65
	v_mov_b32_e32 v50, v65
	v_mov_b32_e32 v51, v65
	v_mov_b32_e32 v56, 0
	v_mov_b32_e32 v57, v65
	v_mov_b32_e32 v58, v65
	v_mov_b32_e32 v59, v65
	v_mov_b32_e32 v52, 0
	v_mov_b32_e32 v53, v65
	v_mov_b32_e32 v54, v65
	v_mov_b32_e32 v55, v65
	v_mov_b32_e32 v60, 0
	v_mov_b32_e32 v61, v65
	v_mov_b32_e32 v62, v65
	v_mov_b32_e32 v63, v65
	s_nop 1
	v_readfirstlane_b32 s84, v66
	v_readfirstlane_b32 s85, v67
	v_readfirstlane_b32 s98, v74
	v_readfirstlane_b32 s99, v75
	v_readfirstlane_b32 s100, v100
	s_nop 1
	s_sub_u32 s84, s84, 0x80
	s_subb_u32 s85, s85, 0
	s_sub_u32 s98, s98, 0x80
	s_subb_u32 s99, s99, 0
	v_subrev_u32_e32 v66, s84, v66
	v_subrev_u32_e32 v68, s84, v68
	v_subrev_u32_e32 v70, s84, v70
	v_subrev_u32_e32 v72, s84, v72
	v_subrev_u32_e32 v74, s98, v74
	v_subrev_u32_e32 v76, s98, v76
	v_subrev_u32_e32 v78, s98, v78
	v_subrev_u32_e32 v80, s98, v80
	s_add_u32 s84, s84, 0x80
	s_addc_u32 s85, s85, 0x0
	s_add_u32 s98, s98, 0x13c0080
	s_addc_u32 s99, s99, 0x0
	s_branch .LBB0_884
.LBB0_883:
	ds_read_b128 v[82:85], v115 offset:32768
	ds_read_b128 v[86:89], v115 offset:34816
	ds_read_b128 v[90:93], v115 offset:36864
	ds_read_b128 v[94:97], v115 offset:38912
	ds_read_b128 v[120:123], v116 offset:49152
	ds_read_b128 v[124:127], v116 offset:51200
	ds_read_b128 v[128:131], v116 offset:53248
	ds_read_b128 v[132:135], v116 offset:55296
	ds_read_b128 v[136:139], v117 offset:32768
	ds_read_b128 v[140:143], v117 offset:34816
	ds_read_b128 v[144:147], v117 offset:36864
	ds_read_b128 v[148:151], v117 offset:38912
	ds_read_b128 v[152:155], v118 offset:49152
	ds_read_b128 v[156:159], v118 offset:51200
	ds_read_b128 v[160:163], v118 offset:53248
	ds_read_b128 v[164:167], v118 offset:55296
	s_add_i32 s11, s11, 2
	s_waitcnt lgkmcnt(0)
	v_mfma_f32_16x16x32_f16 v[0:3], v[120:123], v[82:85], v[0:3]
	v_mfma_f32_16x16x32_f16 v[4:7], v[124:127], v[82:85], v[4:7]
	v_mfma_f32_16x16x32_f16 v[8:11], v[128:131], v[82:85], v[8:11]
	v_mfma_f32_16x16x32_f16 v[12:15], v[132:135], v[82:85], v[12:15]
	v_mfma_f32_16x16x32_f16 v[16:19], v[120:123], v[86:89], v[16:19]
	v_mfma_f32_16x16x32_f16 v[20:23], v[124:127], v[86:89], v[20:23]
	v_mfma_f32_16x16x32_f16 v[24:27], v[128:131], v[86:89], v[24:27]
	v_mfma_f32_16x16x32_f16 v[28:31], v[132:135], v[86:89], v[28:31]
	v_mfma_f32_16x16x32_f16 v[82:85], v[120:123], v[90:93], v[32:35]
	v_mfma_f32_16x16x32_f16 v[86:89], v[124:127], v[90:93], v[36:39]
	v_mfma_f32_16x16x32_f16 v[168:171], v[128:131], v[90:93], v[40:43]
	v_mfma_f32_16x16x32_f16 v[90:93], v[132:135], v[90:93], v[44:47]
	v_mfma_f32_16x16x32_f16 v[120:123], v[120:123], v[94:97], v[48:51]
	v_mfma_f32_16x16x32_f16 v[124:127], v[124:127], v[94:97], v[52:55]
	v_mfma_f32_16x16x32_f16 v[128:131], v[128:131], v[94:97], v[56:59]
	v_mfma_f32_16x16x32_f16 v[94:97], v[132:135], v[94:97], v[60:63]
	v_mfma_f32_16x16x32_f16 v[60:63], v[152:155], v[136:139], v[0:3]
	v_mfma_f32_16x16x32_f16 v[52:55], v[156:159], v[136:139], v[4:7]
	v_mfma_f32_16x16x32_f16 v[56:59], v[160:163], v[136:139], v[8:11]
	v_mfma_f32_16x16x32_f16 v[48:51], v[164:167], v[136:139], v[12:15]
	v_mfma_f32_16x16x32_f16 v[44:47], v[152:155], v[140:143], v[16:19]
	v_mfma_f32_16x16x32_f16 v[36:39], v[156:159], v[140:143], v[20:23]
	v_mfma_f32_16x16x32_f16 v[40:43], v[160:163], v[140:143], v[24:27]
	v_mfma_f32_16x16x32_f16 v[32:35], v[164:167], v[140:143], v[28:31]
	v_mfma_f32_16x16x32_f16 v[28:31], v[152:155], v[144:147], v[82:85]
	v_mfma_f32_16x16x32_f16 v[20:23], v[156:159], v[144:147], v[86:89]
	v_mfma_f32_16x16x32_f16 v[24:27], v[160:163], v[144:147], v[168:171]
	v_mfma_f32_16x16x32_f16 v[16:19], v[164:167], v[144:147], v[90:93]
	v_mfma_f32_16x16x32_f16 v[12:15], v[152:155], v[148:151], v[120:123]
	v_mfma_f32_16x16x32_f16 v[4:7], v[156:159], v[148:151], v[124:127]
	v_mfma_f32_16x16x32_f16 v[8:11], v[160:163], v[148:151], v[128:131]
	v_mfma_f32_16x16x32_f16 v[0:3], v[164:167], v[148:151], v[94:97]
	s_andn2_b64 vcc, exec, s[88:89]
	s_cbranch_vccz .LBB0_881
.LBB0_884:
	s_waitcnt vmcnt(0)
	s_waitcnt vmcnt(0) lgkmcnt(0)
	s_barrier
	s_add_i32 m0, s100, 0x8000
	s_nop 0
	global_load_lds_dwordx4 v66, s[84:85]
	s_add_i32 m0, s100, 0x9000
	s_nop 0
	global_load_lds_dwordx4 v68, s[84:85]
	s_add_i32 m0, s100, 0xa000
	s_nop 0
	global_load_lds_dwordx4 v70, s[84:85]
	s_add_i32 m0, s100, 0xb000
	s_nop 0
	global_load_lds_dwordx4 v72, s[84:85]
	s_add_i32 m0, s100, 0xc000
	s_nop 0
	global_load_lds_dwordx4 v74, s[98:99]
	s_add_i32 m0, s100, 0xd000
	s_nop 0
	global_load_lds_dwordx4 v76, s[98:99]
	s_add_i32 m0, s100, 0xe000
	s_nop 0
	global_load_lds_dwordx4 v78, s[98:99]
	s_add_i32 m0, s100, 0xf000
	s_nop 0
	global_load_lds_dwordx4 v80, s[98:99]
	s_add_u32 s84, s84, 0x80
	s_addc_u32 s85, s85, 0
	s_add_u32 s98, s98, 0x80
	s_addc_u32 s99, s99, 0
	ds_read_b128 v[120:123], v115
	ds_read_b128 v[124:127], v115 offset:2048
	ds_read_b128 v[128:131], v115 offset:4096
	ds_read_b128 v[132:135], v115 offset:6144
	ds_read_b128 v[136:139], v116 offset:16384
	ds_read_b128 v[140:143], v116 offset:18432
	ds_read_b128 v[144:147], v116 offset:20480
	ds_read_b128 v[148:151], v116 offset:22528
	ds_read_b128 v[152:155], v117
	ds_read_b128 v[156:159], v117 offset:2048
	ds_read_b128 v[160:163], v117 offset:4096
	ds_read_b128 v[164:167], v117 offset:6144
	ds_read_b128 v[168:171], v118 offset:16384
	ds_read_b128 v[176:179], v118 offset:18432
	ds_read_b128 v[180:183], v118 offset:20480
	ds_read_b128 v[184:187], v118 offset:22528
	s_waitcnt lgkmcnt(0)
	v_mfma_f32_16x16x32_f16 v[60:63], v[136:139], v[120:123], v[60:63]
	v_mfma_f32_16x16x32_f16 v[52:55], v[140:143], v[120:123], v[52:55]
	v_mfma_f32_16x16x32_f16 v[56:59], v[144:147], v[120:123], v[56:59]
	v_mfma_f32_16x16x32_f16 v[48:51], v[148:151], v[120:123], v[48:51]
	v_mfma_f32_16x16x32_f16 v[44:47], v[136:139], v[124:127], v[44:47]
	v_mfma_f32_16x16x32_f16 v[36:39], v[140:143], v[124:127], v[36:39]
	v_mfma_f32_16x16x32_f16 v[40:43], v[144:147], v[124:127], v[40:43]
	v_mfma_f32_16x16x32_f16 v[32:35], v[148:151], v[124:127], v[32:35]
	v_mfma_f32_16x16x32_f16 v[120:123], v[136:139], v[128:131], v[28:31]
	v_mfma_f32_16x16x32_f16 v[124:127], v[140:143], v[128:131], v[20:23]
	v_mfma_f32_16x16x32_f16 v[188:191], v[144:147], v[128:131], v[24:27]
	v_mfma_f32_16x16x32_f16 v[128:131], v[148:151], v[128:131], v[16:19]
	v_mfma_f32_16x16x32_f16 v[136:139], v[136:139], v[132:135], v[12:15]
	v_mfma_f32_16x16x32_f16 v[140:143], v[140:143], v[132:135], v[4:7]
	v_mfma_f32_16x16x32_f16 v[144:147], v[144:147], v[132:135], v[8:11]
	v_mfma_f32_16x16x32_f16 v[132:135], v[148:151], v[132:135], v[0:3]
	v_mfma_f32_16x16x32_f16 v[0:3], v[168:171], v[152:155], v[60:63]
	v_mfma_f32_16x16x32_f16 v[4:7], v[176:179], v[152:155], v[52:55]
	v_mfma_f32_16x16x32_f16 v[8:11], v[180:183], v[152:155], v[56:59]
	v_mfma_f32_16x16x32_f16 v[12:15], v[184:187], v[152:155], v[48:51]
	v_mfma_f32_16x16x32_f16 v[16:19], v[168:171], v[156:159], v[44:47]
	v_mfma_f32_16x16x32_f16 v[20:23], v[176:179], v[156:159], v[36:39]
	v_mfma_f32_16x16x32_f16 v[24:27], v[180:183], v[156:159], v[40:43]
	v_mfma_f32_16x16x32_f16 v[28:31], v[184:187], v[156:159], v[32:35]
	v_mfma_f32_16x16x32_f16 v[32:35], v[168:171], v[160:163], v[120:123]
	v_mfma_f32_16x16x32_f16 v[36:39], v[176:179], v[160:163], v[124:127]
	v_mfma_f32_16x16x32_f16 v[40:43], v[180:183], v[160:163], v[188:191]
	v_mfma_f32_16x16x32_f16 v[44:47], v[184:187], v[160:163], v[128:131]
	v_mfma_f32_16x16x32_f16 v[48:51], v[168:171], v[164:167], v[136:139]
	v_mfma_f32_16x16x32_f16 v[52:55], v[176:179], v[164:167], v[140:143]
	v_mfma_f32_16x16x32_f16 v[56:59], v[180:183], v[164:167], v[144:147]
	v_mfma_f32_16x16x32_f16 v[60:63], v[184:187], v[164:167], v[132:135]
	s_waitcnt vmcnt(0)
	s_cmp_gt_u32 s11, 13
	s_cselect_b64 s[88:89], -1, 0
	s_and_b64 vcc, exec, s[88:89]
	s_waitcnt vmcnt(0)
	s_barrier
	s_cbranch_vccnz .LBB0_883
	s_mov_b32 m0, s100
	s_nop 0
	global_load_lds_dwordx4 v66, s[84:85]
	s_add_i32 m0, s100, 0x1000
	s_nop 0
	global_load_lds_dwordx4 v68, s[84:85]
	s_add_i32 m0, s100, 0x2000
	s_nop 0
	global_load_lds_dwordx4 v70, s[84:85]
	s_add_i32 m0, s100, 0x3000
	s_nop 0
	global_load_lds_dwordx4 v72, s[84:85]
	s_add_i32 m0, s100, 0x4000
	s_nop 0
	global_load_lds_dwordx4 v74, s[98:99]
	s_add_i32 m0, s100, 0x5000
	s_nop 0
	global_load_lds_dwordx4 v76, s[98:99]
	s_add_i32 m0, s100, 0x6000
	s_nop 0
	global_load_lds_dwordx4 v78, s[98:99]
	s_add_i32 m0, s100, 0x7000
	s_nop 0
	global_load_lds_dwordx4 v80, s[98:99]
	s_add_u32 s84, s84, 0x80
	s_addc_u32 s85, s85, 0
	s_add_u32 s98, s98, 0x80
	s_addc_u32 s99, s99, 0
	s_branch .LBB0_883

.Lto_j_b2:
	s_mul_i32 s98, s98, 17
	s_add_u32 s98, s98, s99
	s_lshl_b32 s99, s98, 3
	s_or_b32 s99, s99, s84
	s_mul_hi_i32 s10, s98, 0x78787879
	s_lshr_b32 s11, s10, 31
	s_ashr_i32 s91, s10, 3
	s_add_i32 s91, s91, s11
	v_mov_b32_e32 v0, v174
	s_mul_i32 s10, s91, 0xffffffef
	s_add_i32 s10, s10, s98
	v_bfe_u32 v2, v0, 1, 3
	v_lshrrev_b32_e32 v3, 4, v0
	s_waitcnt vmcnt(5)
	v_bfe_u32 v4, v0, 4, 2
	v_lshlrev_b32_e32 v5, 7, v0
	v_and_b32_e32 v6, 0x780, v5
	v_bitop3_b32 v3, v3, v2, 3 bitop3:0x6c
	v_bitop3_b32 v2, v4, v2, 4 bitop3:0x36
	s_lshl_b32 s10, s10, 3
	v_lshl_or_b32 v7, v3, 4, v6
	v_lshl_or_b32 v6, v2, 4, v6
	v_lshlrev_b32_e32 v2, 6, v0
	s_or_b32 s92, s10, s84
	v_lshrrev_b32_e32 v1, 3, v0
	v_and_b32_e32 v8, 0xffffe000, v2
	s_movk_i32 s93, 0x1600
	v_lshlrev_b32_e32 v2, 4, v0
	s_mul_i32 s10, s92, 0xb0000
	v_mul_lo_u32 v1, v1, s93
	v_xor_b32_e32 v0, v2, v0
	s_movk_i32 s93, 0x70
	v_add_u32_e32 v100, 0, v2
	s_mul_hi_i32 s11, s92, 0xb0000
	s_add_u32 s10, s42, s10
	v_and_or_b32 v64, v0, s93, v1
	v_readfirstlane_b32 s93, v100
	v_add_u32_e32 v101, 0x1000, v100
	s_addc_u32 s11, s43, s11
	s_mov_b32 m0, s93
	v_readfirstlane_b32 s93, v101
	v_add_u32_e32 v102, 0x2000, v100
	global_load_lds_dwordx4 v64, s[10:11]
	v_add_u32_e32 v0, 0x2c000, v64
	s_mov_b32 m0, s93
	v_readfirstlane_b32 s93, v102
	v_add_u32_e32 v103, 0x3000, v100
	global_load_lds_dwordx4 v0, s[10:11]
	v_add_u32_e32 v2, 0x58000, v64
	s_mov_b32 m0, s93
	v_readfirstlane_b32 s93, v103
	s_mul_i32 s35, s91, 0xb0000
	global_load_lds_dwordx4 v2, s[10:11]
	v_add_u32_e32 v4, 0x84000, v64
	s_mov_b32 m0, s93
	v_add_u32_e32 v104, 0x4000, v100
	s_mul_hi_i32 s34, s91, 0xb0000
	s_add_u32 s12, s88, s35
	global_load_lds_dwordx4 v4, s[10:11]
	v_readfirstlane_b32 s10, v104
	v_add_u32_e32 v105, 0x5000, v100
	s_addc_u32 s13, s89, s34
	s_mov_b32 m0, s10
	v_readfirstlane_b32 s10, v105
	v_add_u32_e32 v106, 0x6000, v100
	global_load_lds_dwordx4 v64, s[12:13]
	s_mov_b32 m0, s10
	v_readfirstlane_b32 s10, v106
	v_add_u32_e32 v107, 0x7000, v100
	global_load_lds_dwordx4 v0, s[12:13]
	s_mov_b32 m0, s10
	v_readfirstlane_b32 s10, v107
	global_load_lds_dwordx4 v2, s[12:13]
	s_mov_b32 m0, s10
	s_mul_i32 s10, s91, 0x88
	global_load_lds_dwordx4 v4, s[12:13]
	s_sub_i32 s10, s99, s10
	s_mul_hi_i32 s11, s10, 0xb0000
	s_mul_i32 s10, s10, 0xb0000
	s_add_u32 s10, s42, s10
	v_and_b32_e32 v9, 0x2000, v5
	v_mov_b32_e32 v1, v65
	v_mov_b32_e32 v3, v65
	v_mov_b32_e32 v5, v65
	s_addc_u32 s11, s43, s11
	v_lshl_add_u64 v[66:67], s[10:11], 0, v[64:65]
	v_lshl_add_u64 v[68:69], s[10:11], 0, v[0:1]
	v_lshl_add_u64 v[70:71], s[10:11], 0, v[2:3]
	v_lshl_add_u64 v[72:73], s[10:11], 0, v[4:5]
	s_add_u32 s10, s36, s35
	v_add_u32_e32 v8, 0, v8
	v_add_u32_e32 v9, 0, v9
	s_addc_u32 s11, s37, s34
	v_lshl_add_u64 v[74:75], s[10:11], 0, v[64:65]
	v_lshl_add_u64 v[76:77], s[10:11], 0, v[0:1]
	v_lshl_add_u64 v[78:79], s[10:11], 0, v[2:3]
	v_lshl_add_u64 v[80:81], s[10:11], 0, v[4:5]
	s_mov_b64 s[10:11], 0
	v_add_u32_e32 v64, 0x8000, v100
	v_add_u32_e32 v108, 0x9000, v100
	v_add_u32_e32 v109, 0xa000, v100
	v_add_u32_e32 v110, 0xb000, v100
	v_add_u32_e32 v111, 0xc000, v100
	v_add_u32_e32 v112, 0xd000, v100
	v_add_u32_e32 v113, 0xe000, v100
	v_add_u32_e32 v114, 0xf000, v100
	v_add_u32_e32 v115, v8, v7
	v_add_u32_e32 v116, v9, v7
	v_add_u32_e32 v117, v8, v6
	v_add_u32_e32 v118, v9, v6
	s_mov_b32 s93, 0
	v_mov_b32_e32 v0, 0
	v_mov_b32_e32 v2, v65
	v_mov_b32_e32 v4, 0
	v_mov_b32_e32 v6, v65
	v_mov_b32_e32 v7, v65
	v_mov_b32_e32 v8, 0
	v_mov_b32_e32 v9, v65
	v_mov_b32_e32 v10, v65
	v_mov_b32_e32 v11, v65
	v_mov_b32_e32 v12, 0
	v_mov_b32_e32 v13, v65
	v_mov_b32_e32 v14, v65
	v_mov_b32_e32 v15, v65
	v_mov_b32_e32 v16, 0
	v_mov_b32_e32 v17, v65
	v_mov_b32_e32 v18, v65
	v_mov_b32_e32 v19, v65
	v_mov_b32_e32 v20, 0
	v_mov_b32_e32 v21, v65
	v_mov_b32_e32 v22, v65
	v_mov_b32_e32 v23, v65
	v_mov_b32_e32 v24, 0
	v_mov_b32_e32 v25, v65
	v_mov_b32_e32 v26, v65
	v_mov_b32_e32 v27, v65
	v_mov_b32_e32 v28, 0
	v_mov_b32_e32 v29, v65
	v_mov_b32_e32 v30, v65
	v_mov_b32_e32 v31, v65
	v_mov_b32_e32 v32, 0
	v_mov_b32_e32 v33, v65
	v_mov_b32_e32 v34, v65
	v_mov_b32_e32 v35, v65
	v_mov_b32_e32 v36, 0
	v_mov_b32_e32 v37, v65
	v_mov_b32_e32 v38, v65
	v_mov_b32_e32 v39, v65
	v_mov_b32_e32 v40, 0
	v_mov_b32_e32 v41, v65
	v_mov_b32_e32 v42, v65
	v_mov_b32_e32 v43, v65
	v_mov_b32_e32 v44, 0
	v_mov_b32_e32 v45, v65
	v_mov_b32_e32 v46, v65
	v_mov_b32_e32 v47, v65
	v_mov_b32_e32 v48, 0
	v_mov_b32_e32 v49, v65
	v_mov_b32_e32 v50, v65
	v_mov_b32_e32 v51, v65
	v_mov_b32_e32 v52, 0
	v_mov_b32_e32 v53, v65
	s_waitcnt vmcnt(0)
	v_mov_b32_e32 v54, v65
	v_mov_b32_e32 v55, v65
	v_mov_b32_e32 v56, 0
	v_mov_b32_e32 v57, v65
	v_mov_b32_e32 v58, v65
	v_mov_b32_e32 v59, v65
	v_mov_b32_e32 v60, 0
	v_mov_b32_e32 v61, v65
	v_mov_b32_e32 v62, v65
	v_mov_b32_e32 v63, v65
	s_nop 1
	v_readfirstlane_b32 s10, v66
	v_readfirstlane_b32 s11, v67
	v_readfirstlane_b32 s98, v74
	v_readfirstlane_b32 s99, v75
	v_readfirstlane_b32 s100, v100
	s_nop 1
	s_sub_u32 s10, s10, 0x80
	s_subb_u32 s11, s11, 0
	s_sub_u32 s98, s98, 0x80
	s_subb_u32 s99, s99, 0
	v_subrev_u32_e32 v66, s10, v66
	v_subrev_u32_e32 v68, s10, v68
	v_subrev_u32_e32 v70, s10, v70
	v_subrev_u32_e32 v72, s10, v72
	v_subrev_u32_e32 v74, s98, v74
	v_subrev_u32_e32 v76, s98, v76
	v_subrev_u32_e32 v78, s98, v78
	v_subrev_u32_e32 v80, s98, v80
	s_add_u32 s10, s10, 0x80
	s_addc_u32 s11, s11, 0x0
	s_add_u32 s98, s98, 0x1ec0080
	s_addc_u32 s99, s99, 0x0
	s_branch .LBB0_953
.LBB0_952:
	ds_read_b128 v[82:85], v115 offset:32768
	ds_read_b128 v[86:89], v115 offset:34816
	ds_read_b128 v[90:93], v115 offset:36864
	ds_read_b128 v[94:97], v115 offset:38912
	ds_read_b128 v[120:123], v116 offset:49152
	ds_read_b128 v[124:127], v116 offset:51200
	ds_read_b128 v[128:131], v116 offset:53248
	ds_read_b128 v[132:135], v116 offset:55296
	ds_read_b128 v[136:139], v117 offset:32768
	ds_read_b128 v[140:143], v117 offset:34816
	ds_read_b128 v[144:147], v117 offset:36864
	ds_read_b128 v[148:151], v117 offset:38912
	ds_read_b128 v[152:155], v118 offset:49152
	ds_read_b128 v[156:159], v118 offset:51200
	ds_read_b128 v[160:163], v118 offset:53248
	ds_read_b128 v[164:167], v118 offset:55296
	s_add_i32 s93, s93, 2
	s_waitcnt lgkmcnt(0)
	v_mfma_f32_16x16x32_f16 v[0:3], v[120:123], v[82:85], v[0:3]
	v_mfma_f32_16x16x32_f16 v[4:7], v[124:127], v[82:85], v[4:7]
	v_mfma_f32_16x16x32_f16 v[8:11], v[128:131], v[82:85], v[8:11]
	v_mfma_f32_16x16x32_f16 v[12:15], v[132:135], v[82:85], v[12:15]
	v_mfma_f32_16x16x32_f16 v[16:19], v[120:123], v[86:89], v[16:19]
	v_mfma_f32_16x16x32_f16 v[20:23], v[124:127], v[86:89], v[20:23]
	v_mfma_f32_16x16x32_f16 v[24:27], v[128:131], v[86:89], v[24:27]
	v_mfma_f32_16x16x32_f16 v[28:31], v[132:135], v[86:89], v[28:31]
	v_mfma_f32_16x16x32_f16 v[82:85], v[120:123], v[90:93], v[32:35]
	v_mfma_f32_16x16x32_f16 v[86:89], v[124:127], v[90:93], v[36:39]
	v_mfma_f32_16x16x32_f16 v[168:171], v[128:131], v[90:93], v[40:43]
	v_mfma_f32_16x16x32_f16 v[90:93], v[132:135], v[90:93], v[44:47]
	v_mfma_f32_16x16x32_f16 v[120:123], v[120:123], v[94:97], v[48:51]
	v_mfma_f32_16x16x32_f16 v[124:127], v[124:127], v[94:97], v[52:55]
	v_mfma_f32_16x16x32_f16 v[128:131], v[128:131], v[94:97], v[56:59]
	v_mfma_f32_16x16x32_f16 v[94:97], v[132:135], v[94:97], v[60:63]
	v_mfma_f32_16x16x32_f16 v[60:63], v[152:155], v[136:139], v[0:3]
	v_mfma_f32_16x16x32_f16 v[56:59], v[156:159], v[136:139], v[4:7]
	v_mfma_f32_16x16x32_f16 v[52:55], v[160:163], v[136:139], v[8:11]
	v_mfma_f32_16x16x32_f16 v[48:51], v[164:167], v[136:139], v[12:15]
	v_mfma_f32_16x16x32_f16 v[44:47], v[152:155], v[140:143], v[16:19]
	v_mfma_f32_16x16x32_f16 v[40:43], v[156:159], v[140:143], v[20:23]
	v_mfma_f32_16x16x32_f16 v[36:39], v[160:163], v[140:143], v[24:27]
	v_mfma_f32_16x16x32_f16 v[32:35], v[164:167], v[140:143], v[28:31]
	v_mfma_f32_16x16x32_f16 v[28:31], v[152:155], v[144:147], v[82:85]
	v_mfma_f32_16x16x32_f16 v[24:27], v[156:159], v[144:147], v[86:89]
	v_mfma_f32_16x16x32_f16 v[20:23], v[160:163], v[144:147], v[168:171]
	v_mfma_f32_16x16x32_f16 v[16:19], v[164:167], v[144:147], v[90:93]
	v_mfma_f32_16x16x32_f16 v[12:15], v[152:155], v[148:151], v[120:123]
	v_mfma_f32_16x16x32_f16 v[8:11], v[156:159], v[148:151], v[124:127]
	v_mfma_f32_16x16x32_f16 v[4:7], v[160:163], v[148:151], v[128:131]
	v_mfma_f32_16x16x32_f16 v[0:3], v[164:167], v[148:151], v[94:97]
	s_andn2_b64 vcc, exec, s[12:13]
	s_cbranch_vccz .LBB0_950
.LBB0_953:
	s_waitcnt vmcnt(0)
	s_waitcnt lgkmcnt(0)
	s_barrier
	s_add_i32 m0, s100, 0x8000
	s_nop 0
	global_load_lds_dwordx4 v66, s[10:11]
	s_add_i32 m0, s100, 0x9000
	s_nop 0
	global_load_lds_dwordx4 v68, s[10:11]
	s_add_i32 m0, s100, 0xa000
	s_nop 0
	global_load_lds_dwordx4 v70, s[10:11]
	s_add_i32 m0, s100, 0xb000
	s_nop 0
	global_load_lds_dwordx4 v72, s[10:11]
	s_add_i32 m0, s100, 0xc000
	s_nop 0
	global_load_lds_dwordx4 v74, s[98:99]
	s_add_i32 m0, s100, 0xd000
	s_nop 0
	global_load_lds_dwordx4 v76, s[98:99]
	s_add_i32 m0, s100, 0xe000
	s_nop 0
	global_load_lds_dwordx4 v78, s[98:99]
	s_add_i32 m0, s100, 0xf000
	s_nop 0
	global_load_lds_dwordx4 v80, s[98:99]
	s_add_u32 s10, s10, 0x80
	s_addc_u32 s11, s11, 0
	s_add_u32 s98, s98, 0x80
	s_addc_u32 s99, s99, 0
	ds_read_b128 v[120:123], v115
	ds_read_b128 v[124:127], v115 offset:2048
	ds_read_b128 v[128:131], v115 offset:4096
	ds_read_b128 v[132:135], v115 offset:6144
	ds_read_b128 v[136:139], v116 offset:16384
	ds_read_b128 v[140:143], v116 offset:18432
	ds_read_b128 v[144:147], v116 offset:20480
	ds_read_b128 v[148:151], v116 offset:22528
	ds_read_b128 v[152:155], v117
	ds_read_b128 v[156:159], v117 offset:2048
	ds_read_b128 v[160:163], v117 offset:4096
	ds_read_b128 v[164:167], v117 offset:6144
	ds_read_b128 v[168:171], v118 offset:16384
	ds_read_b128 v[176:179], v118 offset:18432
	ds_read_b128 v[180:183], v118 offset:20480
	ds_read_b128 v[184:187], v118 offset:22528
	s_waitcnt lgkmcnt(0)
	v_mfma_f32_16x16x32_f16 v[60:63], v[136:139], v[120:123], v[60:63]
	v_mfma_f32_16x16x32_f16 v[56:59], v[140:143], v[120:123], v[56:59]
	v_mfma_f32_16x16x32_f16 v[52:55], v[144:147], v[120:123], v[52:55]
	v_mfma_f32_16x16x32_f16 v[48:51], v[148:151], v[120:123], v[48:51]
	v_mfma_f32_16x16x32_f16 v[44:47], v[136:139], v[124:127], v[44:47]
	v_mfma_f32_16x16x32_f16 v[40:43], v[140:143], v[124:127], v[40:43]
	v_mfma_f32_16x16x32_f16 v[36:39], v[144:147], v[124:127], v[36:39]
	v_mfma_f32_16x16x32_f16 v[32:35], v[148:151], v[124:127], v[32:35]
	v_mfma_f32_16x16x32_f16 v[120:123], v[136:139], v[128:131], v[28:31]
	v_mfma_f32_16x16x32_f16 v[124:127], v[140:143], v[128:131], v[24:27]
	v_mfma_f32_16x16x32_f16 v[188:191], v[144:147], v[128:131], v[20:23]
	v_mfma_f32_16x16x32_f16 v[128:131], v[148:151], v[128:131], v[16:19]
	v_mfma_f32_16x16x32_f16 v[136:139], v[136:139], v[132:135], v[12:15]
	v_mfma_f32_16x16x32_f16 v[140:143], v[140:143], v[132:135], v[8:11]
	v_mfma_f32_16x16x32_f16 v[144:147], v[144:147], v[132:135], v[4:7]
	v_mfma_f32_16x16x32_f16 v[132:135], v[148:151], v[132:135], v[0:3]
	v_mfma_f32_16x16x32_f16 v[0:3], v[168:171], v[152:155], v[60:63]
	v_mfma_f32_16x16x32_f16 v[4:7], v[176:179], v[152:155], v[56:59]
	v_mfma_f32_16x16x32_f16 v[8:11], v[180:183], v[152:155], v[52:55]
	v_mfma_f32_16x16x32_f16 v[12:15], v[184:187], v[152:155], v[48:51]
	v_mfma_f32_16x16x32_f16 v[16:19], v[168:171], v[156:159], v[44:47]
	v_mfma_f32_16x16x32_f16 v[20:23], v[176:179], v[156:159], v[40:43]
	v_mfma_f32_16x16x32_f16 v[24:27], v[180:183], v[156:159], v[36:39]
	v_mfma_f32_16x16x32_f16 v[28:31], v[184:187], v[156:159], v[32:35]
	v_mfma_f32_16x16x32_f16 v[32:35], v[168:171], v[160:163], v[120:123]
	v_mfma_f32_16x16x32_f16 v[36:39], v[176:179], v[160:163], v[124:127]
	v_mfma_f32_16x16x32_f16 v[40:43], v[180:183], v[160:163], v[188:191]
	v_mfma_f32_16x16x32_f16 v[44:47], v[184:187], v[160:163], v[128:131]
	v_mfma_f32_16x16x32_f16 v[48:51], v[168:171], v[164:167], v[136:139]
	v_mfma_f32_16x16x32_f16 v[52:55], v[176:179], v[164:167], v[140:143]
	v_mfma_f32_16x16x32_f16 v[56:59], v[180:183], v[164:167], v[144:147]
	v_mfma_f32_16x16x32_f16 v[60:63], v[184:187], v[164:167], v[132:135]
	s_waitcnt vmcnt(0)
	s_cmp_gt_u32 s93, 41
	s_cselect_b64 s[12:13], -1, 0
	s_and_b64 vcc, exec, s[12:13]
	s_waitcnt vmcnt(0)
	s_barrier
	s_cbranch_vccnz .LBB0_952
	s_mov_b32 m0, s100
	s_nop 0
	global_load_lds_dwordx4 v66, s[10:11]
	s_add_i32 m0, s100, 0x1000
	s_nop 0
	global_load_lds_dwordx4 v68, s[10:11]
	s_add_i32 m0, s100, 0x2000
	s_nop 0
	global_load_lds_dwordx4 v70, s[10:11]
	s_add_i32 m0, s100, 0x3000
	s_nop 0
	global_load_lds_dwordx4 v72, s[10:11]
	s_add_i32 m0, s100, 0x4000
	s_nop 0
	global_load_lds_dwordx4 v74, s[98:99]
	s_add_i32 m0, s100, 0x5000
	s_nop 0
	global_load_lds_dwordx4 v76, s[98:99]
	s_add_i32 m0, s100, 0x6000
	s_nop 0
	global_load_lds_dwordx4 v78, s[98:99]
	s_add_i32 m0, s100, 0x7000
	s_nop 0
	global_load_lds_dwordx4 v80, s[98:99]
	s_add_u32 s10, s10, 0x80
	s_addc_u32 s11, s11, 0
	s_add_u32 s98, s98, 0x80
	s_addc_u32 s99, s99, 0
	s_branch .LBB0_952

.Lto_j_a1:
	s_mul_i32 s98, s98, 17
	s_add_u32 s98, s98, s99
	s_lshl_b32 s99, s98, 3
	s_or_b32 s99, s99, s18
	s_mul_hi_i32 s6, s98, 0x78787879
	s_lshr_b32 s7, s6, 31
	s_ashr_i32 s6, s6, 3
	s_add_i32 s6, s6, s7
	s_mul_i32 s7, s6, 0xffffffef
	s_add_i32 s7, s7, s98
	s_lshl_b32 s7, s7, 3
	s_or_b32 s8, s7, s18
	v_mov_b32_e32 v0, v174
	s_ashr_i32 s9, s8, 31
	s_lshl_b64 s[10:11], s[8:9], 18
	v_bfe_u32 v2, v0, 1, 3
	v_lshrrev_b32_e32 v3, 4, v0
	v_bfe_u32 v4, v0, 4, 2
	v_lshlrev_b32_e32 v5, 7, v0
	v_and_b32_e32 v6, 0x780, v5
	v_bitop3_b32 v3, v3, v2, 3 bitop3:0x6c
	v_bitop3_b32 v2, v4, v2, 4 bitop3:0x36
	s_add_u32 s10, s38, s10
	v_lshl_or_b32 v7, v3, 4, v6
	v_lshl_or_b32 v6, v2, 4, v6
	v_lshlrev_b32_e32 v2, 6, v0
	s_addc_u32 s11, s39, s11
	s_ashr_i32 s7, s6, 31
	v_lshlrev_b32_e32 v1, 8, v0
	v_and_b32_e32 v8, 0xffffe000, v2
	v_lshlrev_b32_e32 v2, 4, v0
	s_lshl_b64 s[12:13], s[6:7], 18
	v_and_b32_e32 v1, 0xfffff800, v1
	v_xor_b32_e32 v0, v2, v0
	s_movk_i32 s7, 0x70
	v_add_u32_e32 v100, 0, v2
	v_and_or_b32 v64, v0, s7, v1
	v_readfirstlane_b32 s7, v100
	v_add_u32_e32 v101, 0x1000, v100
	s_mov_b32 m0, s7
	v_readfirstlane_b32 s7, v101
	v_add_u32_e32 v102, 0x2000, v100
	global_load_lds_dwordx4 v64, s[10:11]
	v_add_u32_e32 v0, 0x10000, v64
	s_mov_b32 m0, s7
	v_readfirstlane_b32 s7, v102
	v_add_u32_e32 v103, 0x3000, v100
	global_load_lds_dwordx4 v0, s[10:11]
	v_add_u32_e32 v2, 0x20000, v64
	s_mov_b32 m0, s7
	v_readfirstlane_b32 s7, v103
	v_add_u32_e32 v104, 0x4000, v100
	s_add_u32 s12, s36, s12
	global_load_lds_dwordx4 v2, s[10:11]
	v_add_u32_e32 v4, 0x30000, v64
	s_mov_b32 m0, s7
	v_readfirstlane_b32 s7, v104
	v_add_u32_e32 v105, 0x5000, v100
	s_addc_u32 s13, s37, s13
	global_load_lds_dwordx4 v4, s[10:11]
	s_mov_b32 m0, s7
	v_readfirstlane_b32 s7, v105
	v_add_u32_e32 v106, 0x6000, v100
	global_load_lds_dwordx4 v64, s[12:13]
	s_mov_b32 m0, s7
	v_readfirstlane_b32 s7, v106
	v_add_u32_e32 v107, 0x7000, v100
	global_load_lds_dwordx4 v0, s[12:13]
	s_mov_b32 m0, s7
	v_readfirstlane_b32 s7, v107
	global_load_lds_dwordx4 v2, s[12:13]
	s_mov_b32 m0, s7
	s_mul_i32 s7, s6, 0x88
	global_load_lds_dwordx4 v4, s[12:13]
	s_sub_i32 s10, s99, s7
	s_ashr_i32 s11, s10, 31
	s_lshl_b64 s[10:11], s[10:11], 18
	v_and_b32_e32 v9, 0x2000, v5
	s_add_u32 s10, s38, s10
	v_mov_b32_e32 v1, v65
	v_mov_b32_e32 v3, v65
	v_mov_b32_e32 v5, v65
	v_add_u32_e32 v8, 0, v8
	v_add_u32_e32 v9, 0, v9
	s_addc_u32 s11, s39, s11
	v_lshl_add_u64 v[66:67], s[12:13], 0, v[64:65]
	v_lshl_add_u64 v[68:69], s[12:13], 0, v[0:1]
	v_lshl_add_u64 v[70:71], s[12:13], 0, v[2:3]
	v_lshl_add_u64 v[72:73], s[12:13], 0, v[4:5]
	v_lshl_add_u64 v[74:75], s[10:11], 0, v[64:65]
	v_lshl_add_u64 v[76:77], s[10:11], 0, v[0:1]
	v_lshl_add_u64 v[78:79], s[10:11], 0, v[2:3]
	v_lshl_add_u64 v[80:81], s[10:11], 0, v[4:5]
	s_mov_b64 s[10:11], 0
	v_add_u32_e32 v64, 0x8000, v100
	v_add_u32_e32 v108, 0x9000, v100
	v_add_u32_e32 v109, 0xa000, v100
	v_add_u32_e32 v110, 0xb000, v100
	v_add_u32_e32 v111, 0xc000, v100
	v_add_u32_e32 v112, 0xd000, v100
	v_add_u32_e32 v113, 0xe000, v100
	v_add_u32_e32 v114, 0xf000, v100
	v_add_u32_e32 v115, v8, v7
	v_add_u32_e32 v116, v9, v7
	v_add_u32_e32 v117, v8, v6
	v_add_u32_e32 v118, v9, v6
	s_mov_b32 s7, 0
	v_mov_b32_e32 v0, 0
	v_mov_b32_e32 v2, v65
	v_mov_b32_e32 v4, 0
	v_mov_b32_e32 v6, v65
	v_mov_b32_e32 v7, v65
	v_mov_b32_e32 v8, 0
	v_mov_b32_e32 v9, v65
	v_mov_b32_e32 v10, v65
	v_mov_b32_e32 v11, v65
	v_mov_b32_e32 v12, 0
	v_mov_b32_e32 v13, v65
	v_mov_b32_e32 v14, v65
	v_mov_b32_e32 v15, v65
	v_mov_b32_e32 v16, 0
	v_mov_b32_e32 v17, v65
	v_mov_b32_e32 v18, v65
	v_mov_b32_e32 v19, v65
	v_mov_b32_e32 v20, 0
	v_mov_b32_e32 v21, v65
	v_mov_b32_e32 v22, v65
	v_mov_b32_e32 v23, v65
	v_mov_b32_e32 v24, 0
	v_mov_b32_e32 v25, v65
	v_mov_b32_e32 v26, v65
	v_mov_b32_e32 v27, v65
	v_mov_b32_e32 v28, 0
	v_mov_b32_e32 v29, v65
	v_mov_b32_e32 v30, v65
	v_mov_b32_e32 v31, v65
	v_mov_b32_e32 v32, 0
	v_mov_b32_e32 v33, v65
	v_mov_b32_e32 v34, v65
	v_mov_b32_e32 v35, v65
	v_mov_b32_e32 v36, 0
	v_mov_b32_e32 v37, v65
	v_mov_b32_e32 v38, v65
	v_mov_b32_e32 v39, v65
	v_mov_b32_e32 v40, 0
	v_mov_b32_e32 v41, v65
	v_mov_b32_e32 v42, v65
	v_mov_b32_e32 v43, v65
	v_mov_b32_e32 v44, 0
	v_mov_b32_e32 v45, v65
	v_mov_b32_e32 v46, v65
	v_mov_b32_e32 v47, v65
	v_mov_b32_e32 v48, 0
	v_mov_b32_e32 v49, v65
	v_mov_b32_e32 v50, v65
	v_mov_b32_e32 v51, v65
	v_mov_b32_e32 v52, 0
	v_mov_b32_e32 v53, v65
	v_mov_b32_e32 v54, v65
	v_mov_b32_e32 v55, v65
	v_mov_b32_e32 v56, 0
	v_mov_b32_e32 v57, v65
	v_mov_b32_e32 v58, v65
	v_mov_b32_e32 v59, v65
	v_mov_b32_e32 v60, 0
	v_mov_b32_e32 v61, v65
	v_mov_b32_e32 v62, v65
	v_mov_b32_e32 v63, v65
	s_nop 1
	v_readfirstlane_b32 s10, v74
	v_readfirstlane_b32 s11, v75
	v_readfirstlane_b32 s98, v66
	v_readfirstlane_b32 s99, v67
	v_readfirstlane_b32 s100, v100
	s_nop 1
	s_sub_u32 s10, s10, 0x80
	s_subb_u32 s11, s11, 0
	s_sub_u32 s98, s98, 0x80
	s_subb_u32 s99, s99, 0
	v_subrev_u32_e32 v74, s10, v74
	v_subrev_u32_e32 v76, s10, v76
	v_subrev_u32_e32 v78, s10, v78
	v_subrev_u32_e32 v80, s10, v80
	v_subrev_u32_e32 v66, s98, v66
	v_subrev_u32_e32 v68, s98, v68
	v_subrev_u32_e32 v70, s98, v70
	v_subrev_u32_e32 v72, s98, v72
	s_add_u32 s10, s10, 0x80
	s_addc_u32 s11, s11, 0x0
	s_add_u32 s98, s98, 0x80
	s_addc_u32 s99, s99, 0x0
	s_branch .LBB0_1142

.LBB0_1591:
	s_lshr_b32 s98, s3, 3
	s_and_b32 s99, s3, 7
	s_and_b32 s100, s20, 1
	s_lshl_b32 s98, s98, 1
	s_or_b32 s98, s98, s100
	s_lshr_b32 s100, s20, 1
	s_lshl_b32 s99, s99, 2
	s_or_b32 s99, s99, s100
	s_and_b32 s101, s98, 7
	s_lshr_b32 s98, s98, 3
	s_mul_i32 s99, s99, 17
	s_add_u32 s98, s98, s99
	s_lshl_b32 s99, s98, 3
	s_or_b32 s99, s99, s101
	s_mul_hi_i32 s10, s98, 0x78787879
	s_lshr_b32 s11, s10, 31
	s_ashr_i32 s10, s10, 3
	s_add_i32 s10, s10, s11
	s_mul_i32 s11, s10, 0xffffffef
	s_add_i32 s11, s11, s98
	s_lshl_b32 s11, s11, 3
	v_mov_b32_e32 v0, v174
	s_or_b32 s12, s11, s101
	s_ashr_i32 s13, s12, 31
	v_bfe_u32 v2, v0, 1, 3
	v_lshrrev_b32_e32 v3, 4, v0
	v_bfe_u32 v4, v0, 4, 2
	v_lshlrev_b32_e32 v5, 7, v0
	v_and_b32_e32 v6, 0x780, v5
	v_bitop3_b32 v3, v3, v2, 3 bitop3:0x6c
	v_bitop3_b32 v2, v4, v2, 4 bitop3:0x36
	s_lshl_b64 s[16:17], s[12:13], 18
	v_lshl_or_b32 v7, v3, 4, v6
	v_lshl_or_b32 v6, v2, 4, v6
	v_lshlrev_b32_e32 v2, 6, v0
	s_add_u32 s16, s38, s16
	v_and_b32_e32 v8, 0xffffe000, v2
	v_lshlrev_b32_e32 v2, 4, v0
	s_addc_u32 s17, s39, s17
	s_ashr_i32 s11, s10, 31
	v_lshlrev_b32_e32 v1, 8, v0
	v_add_u32_e32 v100, 0, v2
	s_lshl_b64 s[18:19], s[10:11], 18
	v_and_b32_e32 v1, 0xfffff800, v1
	v_xor_b32_e32 v0, v2, v0
	v_readfirstlane_b32 s11, v100
	v_add_u32_e32 v101, 0x1000, v100
	v_and_or_b32 v64, v0, s27, v1
	s_mov_b32 m0, s11
	v_readfirstlane_b32 s11, v101
	v_add_u32_e32 v102, 0x2000, v100
	global_load_lds_dwordx4 v64, s[16:17]
	v_add_u32_e32 v0, 0x10000, v64
	s_mov_b32 m0, s11
	v_readfirstlane_b32 s11, v102
	v_add_u32_e32 v103, 0x3000, v100
	global_load_lds_dwordx4 v0, s[16:17]
	v_add_u32_e32 v2, 0x20000, v64
	s_mov_b32 m0, s11
	v_readfirstlane_b32 s11, v103
	v_add_u32_e32 v104, 0x4000, v100
	s_add_u32 s34, s24, s18
	global_load_lds_dwordx4 v2, s[16:17]
	v_add_u32_e32 v4, 0x30000, v64
	s_mov_b32 m0, s11
	v_readfirstlane_b32 s11, v104
	v_add_u32_e32 v105, 0x5000, v100
	s_addc_u32 s35, s25, s19
	global_load_lds_dwordx4 v4, s[16:17]
	s_mov_b32 m0, s11
	v_readfirstlane_b32 s11, v105
	v_add_u32_e32 v106, 0x6000, v100
	global_load_lds_dwordx4 v64, s[34:35]
	s_mov_b32 m0, s11
	v_readfirstlane_b32 s11, v106
	v_add_u32_e32 v107, 0x7000, v100
	global_load_lds_dwordx4 v0, s[34:35]
	s_mov_b32 m0, s11
	v_readfirstlane_b32 s11, v107
	global_load_lds_dwordx4 v2, s[34:35]
	s_mov_b32 m0, s11
	s_mul_i32 s11, s10, 0x88
	global_load_lds_dwordx4 v4, s[34:35]
	s_sub_i32 s16, s99, s11
	s_ashr_i32 s17, s16, 31
	s_lshl_b64 s[16:17], s[16:17], 18
	s_add_u32 s16, s38, s16
	v_and_b32_e32 v9, 0x2000, v5
	v_mov_b32_e32 v1, v65
	v_mov_b32_e32 v3, v65
	v_mov_b32_e32 v5, v65
	s_addc_u32 s17, s39, s17
	v_lshl_add_u64 v[66:67], s[16:17], 0, v[64:65]
	v_lshl_add_u64 v[68:69], s[16:17], 0, v[0:1]
	v_lshl_add_u64 v[70:71], s[16:17], 0, v[2:3]
	v_lshl_add_u64 v[72:73], s[16:17], 0, v[4:5]
	s_add_u32 s16, s36, s18
	v_add_u32_e32 v8, 0, v8
	v_add_u32_e32 v9, 0, v9
	s_addc_u32 s17, s37, s19
	v_lshl_add_u64 v[74:75], s[16:17], 0, v[64:65]
	v_lshl_add_u64 v[76:77], s[16:17], 0, v[0:1]
	v_lshl_add_u64 v[78:79], s[16:17], 0, v[2:3]
	v_lshl_add_u64 v[80:81], s[16:17], 0, v[4:5]
	s_mov_b64 s[16:17], 0
	v_add_u32_e32 v64, 0x8000, v100
	v_add_u32_e32 v108, 0x9000, v100
	v_add_u32_e32 v109, 0xa000, v100
	v_add_u32_e32 v110, 0xb000, v100
	v_add_u32_e32 v111, 0xc000, v100
	v_add_u32_e32 v112, 0xd000, v100
	v_add_u32_e32 v113, 0xe000, v100
	v_add_u32_e32 v114, 0xf000, v100
	v_add_u32_e32 v115, v8, v7
	v_add_u32_e32 v116, v9, v7
	v_add_u32_e32 v117, v8, v6
	v_add_u32_e32 v118, v9, v6
	s_mov_b32 s11, 0
	v_mov_b32_e32 v0, 0
	v_mov_b32_e32 v2, v65
	v_mov_b32_e32 v4, 0
	v_mov_b32_e32 v6, v65
	v_mov_b32_e32 v7, v65
	v_mov_b32_e32 v8, 0
	v_mov_b32_e32 v9, v65
	v_mov_b32_e32 v10, v65
	v_mov_b32_e32 v11, v65
	v_mov_b32_e32 v12, 0
	v_mov_b32_e32 v13, v65
	v_mov_b32_e32 v14, v65
	v_mov_b32_e32 v15, v65
	v_mov_b32_e32 v16, 0
	v_mov_b32_e32 v17, v65
	v_mov_b32_e32 v18, v65
	v_mov_b32_e32 v19, v65
	v_mov_b32_e32 v20, 0
	v_mov_b32_e32 v21, v65
	v_mov_b32_e32 v22, v65
	v_mov_b32_e32 v23, v65
	v_mov_b32_e32 v24, 0
	v_mov_b32_e32 v25, v65
	v_mov_b32_e32 v26, v65
	v_mov_b32_e32 v27, v65
	v_mov_b32_e32 v28, 0
	v_mov_b32_e32 v29, v65
	v_mov_b32_e32 v30, v65
	v_mov_b32_e32 v31, v65
	v_mov_b32_e32 v32, 0
	v_mov_b32_e32 v33, v65
	v_mov_b32_e32 v34, v65
	v_mov_b32_e32 v35, v65
	v_mov_b32_e32 v36, 0
	v_mov_b32_e32 v37, v65
	v_mov_b32_e32 v38, v65
	v_mov_b32_e32 v39, v65
	v_mov_b32_e32 v40, 0
	v_mov_b32_e32 v41, v65
	v_mov_b32_e32 v42, v65
	v_mov_b32_e32 v43, v65
	v_mov_b32_e32 v44, 0
	v_mov_b32_e32 v45, v65
	v_mov_b32_e32 v46, v65
	v_mov_b32_e32 v47, v65
	v_mov_b32_e32 v48, 0
	v_mov_b32_e32 v49, v65
	v_mov_b32_e32 v50, v65
	v_mov_b32_e32 v51, v65
	v_mov_b32_e32 v52, 0
	v_mov_b32_e32 v53, v65
	v_mov_b32_e32 v54, v65
	v_mov_b32_e32 v55, v65
	v_mov_b32_e32 v56, 0
	v_mov_b32_e32 v57, v65
	v_mov_b32_e32 v58, v65
	v_mov_b32_e32 v59, v65
	v_mov_b32_e32 v60, 0
	v_mov_b32_e32 v61, v65
	v_mov_b32_e32 v62, v65
	v_mov_b32_e32 v63, v65
	s_nop 1
	v_readfirstlane_b32 s16, v66
	v_readfirstlane_b32 s17, v67
	v_readfirstlane_b32 s98, v74
	v_readfirstlane_b32 s99, v75
	v_readfirstlane_b32 s100, v100
	s_nop 1
	s_sub_u32 s16, s16, 0x80
	s_subb_u32 s17, s17, 0
	s_sub_u32 s98, s98, 0x80
	s_subb_u32 s99, s99, 0
	v_subrev_u32_e32 v66, s16, v66
	v_subrev_u32_e32 v68, s16, v68
	v_subrev_u32_e32 v70, s16, v70
	v_subrev_u32_e32 v72, s16, v72
	v_subrev_u32_e32 v74, s98, v74
	v_subrev_u32_e32 v76, s98, v76
	v_subrev_u32_e32 v78, s98, v78
	v_subrev_u32_e32 v80, s98, v80
	s_add_u32 s16, s16, 0x80
	s_addc_u32 s17, s17, 0x0
	s_add_u32 s98, s98, 0x7c0080
	s_addc_u32 s99, s99, 0x0
	s_branch .LBB0_1593
.LBB0_1592:
	ds_read_b128 v[82:85], v115 offset:32768
	ds_read_b128 v[86:89], v115 offset:34816
	ds_read_b128 v[90:93], v115 offset:36864
	ds_read_b128 v[94:97], v115 offset:38912
	ds_read_b128 v[120:123], v116 offset:49152
	ds_read_b128 v[124:127], v116 offset:51200
	ds_read_b128 v[128:131], v116 offset:53248
	ds_read_b128 v[132:135], v116 offset:55296
	ds_read_b128 v[136:139], v117 offset:32768
	ds_read_b128 v[140:143], v117 offset:34816
	ds_read_b128 v[144:147], v117 offset:36864
	ds_read_b128 v[148:151], v117 offset:38912
	ds_read_b128 v[152:155], v118 offset:49152
	ds_read_b128 v[156:159], v118 offset:51200
	ds_read_b128 v[160:163], v118 offset:53248
	ds_read_b128 v[164:167], v118 offset:55296
	s_add_i32 s11, s11, 2
	s_waitcnt lgkmcnt(0)
	v_mfma_f32_16x16x32_f16 v[0:3], v[120:123], v[82:85], v[0:3]
	v_mfma_f32_16x16x32_f16 v[4:7], v[124:127], v[82:85], v[4:7]
	v_mfma_f32_16x16x32_f16 v[8:11], v[128:131], v[82:85], v[8:11]
	v_mfma_f32_16x16x32_f16 v[12:15], v[132:135], v[82:85], v[12:15]
	v_mfma_f32_16x16x32_f16 v[16:19], v[120:123], v[86:89], v[16:19]
	v_mfma_f32_16x16x32_f16 v[20:23], v[124:127], v[86:89], v[20:23]
	v_mfma_f32_16x16x32_f16 v[24:27], v[128:131], v[86:89], v[24:27]
	v_mfma_f32_16x16x32_f16 v[28:31], v[132:135], v[86:89], v[28:31]
	v_mfma_f32_16x16x32_f16 v[82:85], v[120:123], v[90:93], v[32:35]
	v_mfma_f32_16x16x32_f16 v[86:89], v[124:127], v[90:93], v[36:39]
	v_mfma_f32_16x16x32_f16 v[168:171], v[128:131], v[90:93], v[40:43]
	v_mfma_f32_16x16x32_f16 v[90:93], v[132:135], v[90:93], v[44:47]
	v_mfma_f32_16x16x32_f16 v[120:123], v[120:123], v[94:97], v[48:51]
	v_mfma_f32_16x16x32_f16 v[124:127], v[124:127], v[94:97], v[52:55]
	v_mfma_f32_16x16x32_f16 v[128:131], v[128:131], v[94:97], v[56:59]
	v_mfma_f32_16x16x32_f16 v[94:97], v[132:135], v[94:97], v[60:63]
	v_mfma_f32_16x16x32_f16 v[60:63], v[152:155], v[136:139], v[0:3]
	v_mfma_f32_16x16x32_f16 v[56:59], v[156:159], v[136:139], v[4:7]
	v_mfma_f32_16x16x32_f16 v[52:55], v[160:163], v[136:139], v[8:11]
	v_mfma_f32_16x16x32_f16 v[48:51], v[164:167], v[136:139], v[12:15]
	v_mfma_f32_16x16x32_f16 v[44:47], v[152:155], v[140:143], v[16:19]
	v_mfma_f32_16x16x32_f16 v[40:43], v[156:159], v[140:143], v[20:23]
	v_mfma_f32_16x16x32_f16 v[36:39], v[160:163], v[140:143], v[24:27]
	v_mfma_f32_16x16x32_f16 v[32:35], v[164:167], v[140:143], v[28:31]
	v_mfma_f32_16x16x32_f16 v[28:31], v[152:155], v[144:147], v[82:85]
	v_mfma_f32_16x16x32_f16 v[24:27], v[156:159], v[144:147], v[86:89]
	v_mfma_f32_16x16x32_f16 v[20:23], v[160:163], v[144:147], v[168:171]
	v_mfma_f32_16x16x32_f16 v[16:19], v[164:167], v[144:147], v[90:93]
	v_mfma_f32_16x16x32_f16 v[12:15], v[152:155], v[148:151], v[120:123]
	v_mfma_f32_16x16x32_f16 v[8:11], v[156:159], v[148:151], v[124:127]
	v_mfma_f32_16x16x32_f16 v[4:7], v[160:163], v[148:151], v[128:131]
	v_mfma_f32_16x16x32_f16 v[0:3], v[164:167], v[148:151], v[94:97]
	s_andn2_b64 vcc, exec, s[18:19]
	s_cbranch_vccz .LBB0_1590
.LBB0_1593:
	s_waitcnt vmcnt(0)
	s_waitcnt vmcnt(0) lgkmcnt(0)
	s_barrier
	s_add_i32 m0, s100, 0x8000
	s_nop 0
	global_load_lds_dwordx4 v66, s[16:17]
	s_add_i32 m0, s100, 0x9000
	s_nop 0
	global_load_lds_dwordx4 v68, s[16:17]
	s_add_i32 m0, s100, 0xa000
	s_nop 0
	global_load_lds_dwordx4 v70, s[16:17]
	s_add_i32 m0, s100, 0xb000
	s_nop 0
	global_load_lds_dwordx4 v72, s[16:17]
	s_add_i32 m0, s100, 0xc000
	s_nop 0
	global_load_lds_dwordx4 v74, s[98:99]
	s_add_i32 m0, s100, 0xd000
	s_nop 0
	global_load_lds_dwordx4 v76, s[98:99]
	s_add_i32 m0, s100, 0xe000
	s_nop 0
	global_load_lds_dwordx4 v78, s[98:99]
	s_add_i32 m0, s100, 0xf000
	s_nop 0
	global_load_lds_dwordx4 v80, s[98:99]
	s_add_u32 s16, s16, 0x80
	s_addc_u32 s17, s17, 0
	s_add_u32 s98, s98, 0x80
	s_addc_u32 s99, s99, 0
	ds_read_b128 v[120:123], v115
	ds_read_b128 v[124:127], v115 offset:2048
	ds_read_b128 v[128:131], v115 offset:4096
	ds_read_b128 v[132:135], v115 offset:6144
	ds_read_b128 v[136:139], v116 offset:16384
	ds_read_b128 v[140:143], v116 offset:18432
	ds_read_b128 v[144:147], v116 offset:20480
	ds_read_b128 v[148:151], v116 offset:22528
	ds_read_b128 v[152:155], v117
	ds_read_b128 v[156:159], v117 offset:2048
	ds_read_b128 v[160:163], v117 offset:4096
	ds_read_b128 v[164:167], v117 offset:6144
	ds_read_b128 v[168:171], v118 offset:16384
	ds_read_b128 v[176:179], v118 offset:18432
	ds_read_b128 v[180:183], v118 offset:20480
	ds_read_b128 v[184:187], v118 offset:22528
	s_waitcnt lgkmcnt(0)
	v_mfma_f32_16x16x32_f16 v[60:63], v[136:139], v[120:123], v[60:63]
	v_mfma_f32_16x16x32_f16 v[56:59], v[140:143], v[120:123], v[56:59]
	v_mfma_f32_16x16x32_f16 v[52:55], v[144:147], v[120:123], v[52:55]
	v_mfma_f32_16x16x32_f16 v[48:51], v[148:151], v[120:123], v[48:51]
	v_mfma_f32_16x16x32_f16 v[44:47], v[136:139], v[124:127], v[44:47]
	v_mfma_f32_16x16x32_f16 v[40:43], v[140:143], v[124:127], v[40:43]
	v_mfma_f32_16x16x32_f16 v[36:39], v[144:147], v[124:127], v[36:39]
	v_mfma_f32_16x16x32_f16 v[32:35], v[148:151], v[124:127], v[32:35]
	v_mfma_f32_16x16x32_f16 v[120:123], v[136:139], v[128:131], v[28:31]
	v_mfma_f32_16x16x32_f16 v[124:127], v[140:143], v[128:131], v[24:27]
	v_mfma_f32_16x16x32_f16 v[188:191], v[144:147], v[128:131], v[20:23]
	v_mfma_f32_16x16x32_f16 v[128:131], v[148:151], v[128:131], v[16:19]
	v_mfma_f32_16x16x32_f16 v[136:139], v[136:139], v[132:135], v[12:15]
	v_mfma_f32_16x16x32_f16 v[140:143], v[140:143], v[132:135], v[8:11]
	v_mfma_f32_16x16x32_f16 v[144:147], v[144:147], v[132:135], v[4:7]
	v_mfma_f32_16x16x32_f16 v[132:135], v[148:151], v[132:135], v[0:3]
	v_mfma_f32_16x16x32_f16 v[0:3], v[168:171], v[152:155], v[60:63]
	v_mfma_f32_16x16x32_f16 v[4:7], v[176:179], v[152:155], v[56:59]
	v_mfma_f32_16x16x32_f16 v[8:11], v[180:183], v[152:155], v[52:55]
	v_mfma_f32_16x16x32_f16 v[12:15], v[184:187], v[152:155], v[48:51]
	v_mfma_f32_16x16x32_f16 v[16:19], v[168:171], v[156:159], v[44:47]
	v_mfma_f32_16x16x32_f16 v[20:23], v[176:179], v[156:159], v[40:43]
	v_mfma_f32_16x16x32_f16 v[24:27], v[180:183], v[156:159], v[36:39]
	v_mfma_f32_16x16x32_f16 v[28:31], v[184:187], v[156:159], v[32:35]
	v_mfma_f32_16x16x32_f16 v[32:35], v[168:171], v[160:163], v[120:123]
	v_mfma_f32_16x16x32_f16 v[36:39], v[176:179], v[160:163], v[124:127]
	v_mfma_f32_16x16x32_f16 v[40:43], v[180:183], v[160:163], v[188:191]
	v_mfma_f32_16x16x32_f16 v[44:47], v[184:187], v[160:163], v[128:131]
	v_mfma_f32_16x16x32_f16 v[48:51], v[168:171], v[164:167], v[136:139]
	v_mfma_f32_16x16x32_f16 v[52:55], v[176:179], v[164:167], v[140:143]
	v_mfma_f32_16x16x32_f16 v[56:59], v[180:183], v[164:167], v[144:147]
	v_mfma_f32_16x16x32_f16 v[60:63], v[184:187], v[164:167], v[132:135]
	s_waitcnt vmcnt(0)
	s_cmp_gt_u32 s11, 13
	s_cselect_b64 s[18:19], -1, 0
	s_and_b64 vcc, exec, s[18:19]
	s_waitcnt vmcnt(0)
	s_barrier
	s_cbranch_vccnz .LBB0_1592
	s_mov_b32 m0, s100
	s_nop 0
	global_load_lds_dwordx4 v66, s[16:17]
	s_add_i32 m0, s100, 0x1000
	s_nop 0
	global_load_lds_dwordx4 v68, s[16:17]
	s_add_i32 m0, s100, 0x2000
	s_nop 0
	global_load_lds_dwordx4 v70, s[16:17]
	s_add_i32 m0, s100, 0x3000
	s_nop 0
	global_load_lds_dwordx4 v72, s[16:17]
	s_add_i32 m0, s100, 0x4000
	s_nop 0
	global_load_lds_dwordx4 v74, s[98:99]
	s_add_i32 m0, s100, 0x5000
	s_nop 0
	global_load_lds_dwordx4 v76, s[98:99]
	s_add_i32 m0, s100, 0x6000
	s_nop 0
	global_load_lds_dwordx4 v78, s[98:99]
	s_add_i32 m0, s100, 0x7000
	s_nop 0
	global_load_lds_dwordx4 v80, s[98:99]
	s_add_u32 s16, s16, 0x80
	s_addc_u32 s17, s17, 0
	s_add_u32 s98, s98, 0x80
	s_addc_u32 s99, s99, 0
	s_branch .LBB0_1592

.Lto_j_b4:
	s_mul_i32 s98, s98, 17
	s_add_u32 s98, s98, s99
	s_lshl_b32 s99, s98, 3
	s_or_b32 s99, s99, s20
	s_mul_hi_i32 s10, s98, 0x78787879
	s_lshr_b32 s11, s10, 31
	s_ashr_i32 s10, s10, 3
	s_add_i32 s10, s10, s11
	s_mul_i32 s11, s10, 0xffffffef
	s_add_i32 s11, s11, s98
	s_lshl_b32 s11, s11, 3
	v_mov_b32_e32 v0, v174
	s_or_b32 s12, s11, s20
	s_ashr_i32 s13, s12, 31
	v_bfe_u32 v2, v0, 1, 3
	v_lshrrev_b32_e32 v3, 4, v0
	s_waitcnt vmcnt(5)
	v_bfe_u32 v4, v0, 4, 2
	v_lshlrev_b32_e32 v5, 7, v0
	v_and_b32_e32 v6, 0x780, v5
	v_bitop3_b32 v3, v3, v2, 3 bitop3:0x6c
	v_bitop3_b32 v2, v4, v2, 4 bitop3:0x36
	s_lshl_b64 s[16:17], s[12:13], 18
	v_lshl_or_b32 v7, v3, 4, v6
	v_lshl_or_b32 v6, v2, 4, v6
	v_lshlrev_b32_e32 v2, 6, v0
	s_add_u32 s16, s38, s16
	v_and_b32_e32 v8, 0xffffe000, v2
	v_lshlrev_b32_e32 v2, 4, v0
	s_addc_u32 s17, s39, s17
	s_ashr_i32 s11, s10, 31
	v_lshlrev_b32_e32 v1, 8, v0
	v_add_u32_e32 v100, 0, v2
	s_lshl_b64 s[18:19], s[10:11], 18
	v_and_b32_e32 v1, 0xfffff800, v1
	v_xor_b32_e32 v0, v2, v0
	v_readfirstlane_b32 s11, v100
	v_add_u32_e32 v101, 0x1000, v100
	v_and_or_b32 v64, v0, s25, v1
	s_mov_b32 m0, s11
	v_readfirstlane_b32 s11, v101
	v_add_u32_e32 v102, 0x2000, v100
	global_load_lds_dwordx4 v64, s[16:17]
	v_add_u32_e32 v0, 0x10000, v64
	s_mov_b32 m0, s11
	v_readfirstlane_b32 s11, v102
	v_add_u32_e32 v103, 0x3000, v100
	global_load_lds_dwordx4 v0, s[16:17]
	v_add_u32_e32 v2, 0x20000, v64
	s_mov_b32 m0, s11
	v_readfirstlane_b32 s11, v103
	v_add_u32_e32 v104, 0x4000, v100
	s_add_u32 s26, s70, s18
	global_load_lds_dwordx4 v2, s[16:17]
	v_add_u32_e32 v4, 0x30000, v64
	s_mov_b32 m0, s11
	v_readfirstlane_b32 s11, v104
	v_add_u32_e32 v105, 0x5000, v100
	s_addc_u32 s27, s71, s19
	global_load_lds_dwordx4 v4, s[16:17]
	s_mov_b32 m0, s11
	v_readfirstlane_b32 s11, v105
	v_add_u32_e32 v106, 0x6000, v100
	global_load_lds_dwordx4 v64, s[26:27]
	s_mov_b32 m0, s11
	v_readfirstlane_b32 s11, v106
	v_add_u32_e32 v107, 0x7000, v100
	global_load_lds_dwordx4 v0, s[26:27]
	s_mov_b32 m0, s11
	v_readfirstlane_b32 s11, v107
	global_load_lds_dwordx4 v2, s[26:27]
	s_mov_b32 m0, s11
	s_mul_i32 s11, s10, 0x88
	global_load_lds_dwordx4 v4, s[26:27]
	s_sub_i32 s16, s99, s11
	s_ashr_i32 s17, s16, 31
	s_lshl_b64 s[16:17], s[16:17], 18
	s_add_u32 s16, s38, s16
	v_and_b32_e32 v9, 0x2000, v5
	v_mov_b32_e32 v1, v65
	v_mov_b32_e32 v3, v65
	v_mov_b32_e32 v5, v65
	s_addc_u32 s17, s39, s17
	v_lshl_add_u64 v[66:67], s[16:17], 0, v[64:65]
	v_lshl_add_u64 v[68:69], s[16:17], 0, v[0:1]
	v_lshl_add_u64 v[70:71], s[16:17], 0, v[2:3]
	v_lshl_add_u64 v[72:73], s[16:17], 0, v[4:5]
	s_add_u32 s16, s36, s18
	v_add_u32_e32 v8, 0, v8
	v_add_u32_e32 v9, 0, v9
	s_addc_u32 s17, s37, s19
	v_lshl_add_u64 v[74:75], s[16:17], 0, v[64:65]
	v_lshl_add_u64 v[76:77], s[16:17], 0, v[0:1]
	v_lshl_add_u64 v[78:79], s[16:17], 0, v[2:3]
	v_lshl_add_u64 v[80:81], s[16:17], 0, v[4:5]
	s_mov_b64 s[16:17], 0
	v_add_u32_e32 v64, 0x8000, v100
	v_add_u32_e32 v108, 0x9000, v100
	v_add_u32_e32 v109, 0xa000, v100
	v_add_u32_e32 v110, 0xb000, v100
	v_add_u32_e32 v111, 0xc000, v100
	v_add_u32_e32 v112, 0xd000, v100
	v_add_u32_e32 v113, 0xe000, v100
	v_add_u32_e32 v114, 0xf000, v100
	v_add_u32_e32 v115, v8, v7
	v_add_u32_e32 v116, v9, v7
	v_add_u32_e32 v117, v8, v6
	v_add_u32_e32 v118, v9, v6
	s_mov_b32 s11, 0
	v_mov_b32_e32 v0, 0
	v_mov_b32_e32 v2, v65
	v_mov_b32_e32 v4, 0
	v_mov_b32_e32 v6, v65
	v_mov_b32_e32 v7, v65
	v_mov_b32_e32 v8, 0
	v_mov_b32_e32 v9, v65
	v_mov_b32_e32 v10, v65
	v_mov_b32_e32 v11, v65
	v_mov_b32_e32 v12, 0
	v_mov_b32_e32 v13, v65
	v_mov_b32_e32 v14, v65
	v_mov_b32_e32 v15, v65
	v_mov_b32_e32 v16, 0
	v_mov_b32_e32 v17, v65
	v_mov_b32_e32 v18, v65
	v_mov_b32_e32 v19, v65
	v_mov_b32_e32 v20, 0
	v_mov_b32_e32 v21, v65
	v_mov_b32_e32 v22, v65
	v_mov_b32_e32 v23, v65
	v_mov_b32_e32 v24, 0
	v_mov_b32_e32 v25, v65
	v_mov_b32_e32 v26, v65
	v_mov_b32_e32 v27, v65
	v_mov_b32_e32 v28, 0
	v_mov_b32_e32 v29, v65
	v_mov_b32_e32 v30, v65
	v_mov_b32_e32 v31, v65
	v_mov_b32_e32 v32, 0
	v_mov_b32_e32 v33, v65
	v_mov_b32_e32 v34, v65
	v_mov_b32_e32 v35, v65
	v_mov_b32_e32 v36, 0
	v_mov_b32_e32 v37, v65
	v_mov_b32_e32 v38, v65
	v_mov_b32_e32 v39, v65
	v_mov_b32_e32 v40, 0
	v_mov_b32_e32 v41, v65
	v_mov_b32_e32 v42, v65
	v_mov_b32_e32 v43, v65
	v_mov_b32_e32 v44, 0
	v_mov_b32_e32 v45, v65
	v_mov_b32_e32 v46, v65
	v_mov_b32_e32 v47, v65
	v_mov_b32_e32 v48, 0
	v_mov_b32_e32 v49, v65
	v_mov_b32_e32 v50, v65
	v_mov_b32_e32 v51, v65
	v_mov_b32_e32 v52, 0
	v_mov_b32_e32 v53, v65
	s_waitcnt vmcnt(0)
	v_mov_b32_e32 v54, v65
	v_mov_b32_e32 v55, v65
	v_mov_b32_e32 v56, 0
	v_mov_b32_e32 v57, v65
	v_mov_b32_e32 v58, v65
	v_mov_b32_e32 v59, v65
	v_mov_b32_e32 v60, 0
	v_mov_b32_e32 v61, v65
	v_mov_b32_e32 v62, v65
	v_mov_b32_e32 v63, v65
	s_nop 1
	v_readfirstlane_b32 s16, v66
	v_readfirstlane_b32 s17, v67
	v_readfirstlane_b32 s98, v74
	v_readfirstlane_b32 s99, v75
	v_readfirstlane_b32 s100, v100
	s_nop 1
	s_sub_u32 s16, s16, 0x80
	s_subb_u32 s17, s17, 0
	s_sub_u32 s98, s98, 0x80
	s_subb_u32 s99, s99, 0
	v_subrev_u32_e32 v66, s16, v66
	v_subrev_u32_e32 v68, s16, v68
	v_subrev_u32_e32 v70, s16, v70
	v_subrev_u32_e32 v72, s16, v72
	v_subrev_u32_e32 v74, s98, v74
	v_subrev_u32_e32 v76, s98, v76
	v_subrev_u32_e32 v78, s98, v78
	v_subrev_u32_e32 v80, s98, v80
	s_add_u32 s16, s16, 0x80
	s_addc_u32 s17, s17, 0x0
	s_add_u32 s98, s98, 0x11c0080
	s_addc_u32 s99, s99, 0x0
	s_branch .LBB0_1735

.LBB0_1735:
	s_waitcnt vmcnt(0)
	s_waitcnt lgkmcnt(0)
	s_barrier
	s_add_i32 m0, s100, 0x8000
	s_nop 0
	global_load_lds_dwordx4 v66, s[16:17]
	s_add_i32 m0, s100, 0x9000
	s_nop 0
	global_load_lds_dwordx4 v68, s[16:17]
	s_add_i32 m0, s100, 0xa000
	s_nop 0
	global_load_lds_dwordx4 v70, s[16:17]
	s_add_i32 m0, s100, 0xb000
	s_nop 0
	global_load_lds_dwordx4 v72, s[16:17]
	s_add_i32 m0, s100, 0xc000
	s_nop 0
	global_load_lds_dwordx4 v74, s[98:99]
	s_add_i32 m0, s100, 0xd000
	s_nop 0
	global_load_lds_dwordx4 v76, s[98:99]
	s_add_i32 m0, s100, 0xe000
	s_nop 0
	global_load_lds_dwordx4 v78, s[98:99]
	s_add_i32 m0, s100, 0xf000
	s_nop 0
	global_load_lds_dwordx4 v80, s[98:99]
	s_add_u32 s16, s16, 0x80
	s_addc_u32 s17, s17, 0
	s_add_u32 s98, s98, 0x80
	s_addc_u32 s99, s99, 0
	ds_read_b128 v[120:123], v115
	ds_read_b128 v[124:127], v115 offset:2048
	ds_read_b128 v[128:131], v115 offset:4096
	ds_read_b128 v[132:135], v115 offset:6144
	ds_read_b128 v[136:139], v116 offset:16384
	ds_read_b128 v[140:143], v116 offset:18432
	ds_read_b128 v[144:147], v116 offset:20480
	ds_read_b128 v[148:151], v116 offset:22528
	ds_read_b128 v[152:155], v117
	ds_read_b128 v[156:159], v117 offset:2048
	ds_read_b128 v[160:163], v117 offset:4096
	ds_read_b128 v[164:167], v117 offset:6144
	ds_read_b128 v[168:171], v118 offset:16384
	ds_read_b128 v[176:179], v118 offset:18432
	ds_read_b128 v[180:183], v118 offset:20480
	ds_read_b128 v[184:187], v118 offset:22528
	s_waitcnt lgkmcnt(0)
	v_mfma_f32_16x16x32_f16 v[60:63], v[136:139], v[120:123], v[60:63]
	v_mfma_f32_16x16x32_f16 v[56:59], v[140:143], v[120:123], v[56:59]
	v_mfma_f32_16x16x32_f16 v[52:55], v[144:147], v[120:123], v[52:55]
	v_mfma_f32_16x16x32_f16 v[48:51], v[148:151], v[120:123], v[48:51]
	v_mfma_f32_16x16x32_f16 v[44:47], v[136:139], v[124:127], v[44:47]
	v_mfma_f32_16x16x32_f16 v[40:43], v[140:143], v[124:127], v[40:43]
	v_mfma_f32_16x16x32_f16 v[36:39], v[144:147], v[124:127], v[36:39]
	v_mfma_f32_16x16x32_f16 v[32:35], v[148:151], v[124:127], v[32:35]
	v_mfma_f32_16x16x32_f16 v[120:123], v[136:139], v[128:131], v[28:31]
	v_mfma_f32_16x16x32_f16 v[124:127], v[140:143], v[128:131], v[24:27]
	v_mfma_f32_16x16x32_f16 v[188:191], v[144:147], v[128:131], v[20:23]
	v_mfma_f32_16x16x32_f16 v[128:131], v[148:151], v[128:131], v[16:19]
	v_mfma_f32_16x16x32_f16 v[136:139], v[136:139], v[132:135], v[12:15]
	v_mfma_f32_16x16x32_f16 v[140:143], v[140:143], v[132:135], v[8:11]
	v_mfma_f32_16x16x32_f16 v[144:147], v[144:147], v[132:135], v[4:7]
	v_mfma_f32_16x16x32_f16 v[132:135], v[148:151], v[132:135], v[0:3]
	v_mfma_f32_16x16x32_f16 v[0:3], v[168:171], v[152:155], v[60:63]
	v_mfma_f32_16x16x32_f16 v[4:7], v[176:179], v[152:155], v[56:59]
	v_mfma_f32_16x16x32_f16 v[8:11], v[180:183], v[152:155], v[52:55]
	v_mfma_f32_16x16x32_f16 v[12:15], v[184:187], v[152:155], v[48:51]
	v_mfma_f32_16x16x32_f16 v[16:19], v[168:171], v[156:159], v[44:47]
	v_mfma_f32_16x16x32_f16 v[20:23], v[176:179], v[156:159], v[40:43]
	v_mfma_f32_16x16x32_f16 v[24:27], v[180:183], v[156:159], v[36:39]
	v_mfma_f32_16x16x32_f16 v[28:31], v[184:187], v[156:159], v[32:35]
	v_mfma_f32_16x16x32_f16 v[32:35], v[168:171], v[160:163], v[120:123]
	v_mfma_f32_16x16x32_f16 v[36:39], v[176:179], v[160:163], v[124:127]
	v_mfma_f32_16x16x32_f16 v[40:43], v[180:183], v[160:163], v[188:191]
	v_mfma_f32_16x16x32_f16 v[44:47], v[184:187], v[160:163], v[128:131]
	v_mfma_f32_16x16x32_f16 v[48:51], v[168:171], v[164:167], v[136:139]
	v_mfma_f32_16x16x32_f16 v[52:55], v[176:179], v[164:167], v[140:143]
	v_mfma_f32_16x16x32_f16 v[56:59], v[180:183], v[164:167], v[144:147]
	v_mfma_f32_16x16x32_f16 v[60:63], v[184:187], v[164:167], v[132:135]
	s_waitcnt vmcnt(0)
	s_cmp_gt_u32 s11, 13
	s_cselect_b64 s[18:19], -1, 0
	s_and_b64 vcc, exec, s[18:19]
	s_waitcnt vmcnt(0)
	s_barrier
	s_cbranch_vccnz .LBB0_1734
	s_mov_b32 m0, s100
	s_nop 0
	global_load_lds_dwordx4 v66, s[16:17]
	s_add_i32 m0, s100, 0x1000
	s_nop 0
	global_load_lds_dwordx4 v68, s[16:17]
	s_add_i32 m0, s100, 0x2000
	s_nop 0
	global_load_lds_dwordx4 v70, s[16:17]
	s_add_i32 m0, s100, 0x3000
	s_nop 0
	global_load_lds_dwordx4 v72, s[16:17]
	s_add_i32 m0, s100, 0x4000
	s_nop 0
	global_load_lds_dwordx4 v74, s[98:99]
	s_add_i32 m0, s100, 0x5000
	s_nop 0
	global_load_lds_dwordx4 v76, s[98:99]
	s_add_i32 m0, s100, 0x6000
	s_nop 0
	global_load_lds_dwordx4 v78, s[98:99]
	s_add_i32 m0, s100, 0x7000
	s_nop 0
	global_load_lds_dwordx4 v80, s[98:99]
	s_add_u32 s16, s16, 0x80
	s_addc_u32 s17, s17, 0
	s_add_u32 s98, s98, 0x80
	s_addc_u32 s99, s99, 0
	s_branch .LBB0_1734

.LBB0_1865:
	s_mul_hi_u32 s98, s3, 0xba2e8ba3
	s_lshr_b32 s98, s98, 3
	s_mul_i32 s99, s98, 11
	s_sub_u32 s99, s3, s99
	s_and_b32 s100, s20, 1
	s_lshl_b32 s98, s98, 1
	s_or_b32 s98, s98, s100
	s_lshr_b32 s100, s20, 1
	s_lshl_b32 s99, s99, 2
	s_or_b32 s99, s99, s100
	s_and_b32 s101, s98, 7
	s_lshr_b32 s98, s98, 3
	s_mul_i32 s99, s99, 17
	s_add_u32 s98, s98, s99
	s_lshl_b32 s99, s98, 3
	s_or_b32 s99, s99, s101
	s_mul_hi_i32 s10, s98, 0x78787879
	s_lshr_b32 s11, s10, 31
	s_ashr_i32 s10, s10, 3
	s_add_i32 s10, s10, s11
	s_mul_i32 s11, s10, 0xffffffef
	s_add_i32 s11, s11, s98
	s_lshl_b32 s11, s11, 3
	v_mov_b32_e32 v0, v174
	s_or_b32 s12, s11, s101
	s_ashr_i32 s13, s12, 31
	v_bfe_u32 v2, v0, 1, 3
	v_lshrrev_b32_e32 v3, 4, v0
	v_bfe_u32 v4, v0, 4, 2
	v_lshlrev_b32_e32 v5, 7, v0
	v_and_b32_e32 v6, 0x780, v5
	v_bitop3_b32 v3, v3, v2, 3 bitop3:0x6c
	v_bitop3_b32 v2, v4, v2, 4 bitop3:0x36
	s_lshl_b64 s[16:17], s[12:13], 18
	v_lshl_or_b32 v7, v3, 4, v6
	v_lshl_or_b32 v6, v2, 4, v6
	v_lshlrev_b32_e32 v2, 6, v0
	s_add_u32 s16, s38, s16
	v_and_b32_e32 v8, 0xffffe000, v2
	v_lshlrev_b32_e32 v2, 4, v0
	s_addc_u32 s17, s39, s17
	s_ashr_i32 s11, s10, 31
	v_lshlrev_b32_e32 v1, 8, v0
	v_add_u32_e32 v100, 0, v2
	s_lshl_b64 s[18:19], s[10:11], 18
	v_and_b32_e32 v1, 0xfffff800, v1
	v_xor_b32_e32 v0, v2, v0
	v_readfirstlane_b32 s11, v100
	v_add_u32_e32 v101, 0x1000, v100
	v_and_or_b32 v64, v0, s25, v1
	s_mov_b32 m0, s11
	v_readfirstlane_b32 s11, v101
	v_add_u32_e32 v102, 0x2000, v100
	global_load_lds_dwordx4 v64, s[16:17]
	v_add_u32_e32 v0, 0x10000, v64
	s_mov_b32 m0, s11
	v_readfirstlane_b32 s11, v102
	v_add_u32_e32 v103, 0x3000, v100
	global_load_lds_dwordx4 v0, s[16:17]
	v_add_u32_e32 v2, 0x20000, v64
	s_mov_b32 m0, s11
	v_readfirstlane_b32 s11, v103
	v_add_u32_e32 v104, 0x4000, v100
	s_add_u32 s34, s22, s18
	global_load_lds_dwordx4 v2, s[16:17]
	v_add_u32_e32 v4, 0x30000, v64
	s_mov_b32 m0, s11
	v_readfirstlane_b32 s11, v104
	v_add_u32_e32 v105, 0x5000, v100
	s_addc_u32 s35, s23, s19
	global_load_lds_dwordx4 v4, s[16:17]
	s_mov_b32 m0, s11
	v_readfirstlane_b32 s11, v105
	v_add_u32_e32 v106, 0x6000, v100
	global_load_lds_dwordx4 v64, s[34:35]
	s_mov_b32 m0, s11
	v_readfirstlane_b32 s11, v106
	v_add_u32_e32 v107, 0x7000, v100
	global_load_lds_dwordx4 v0, s[34:35]
	s_mov_b32 m0, s11
	v_readfirstlane_b32 s11, v107
	global_load_lds_dwordx4 v2, s[34:35]
	s_mov_b32 m0, s11
	s_mul_i32 s11, s10, 0x88
	global_load_lds_dwordx4 v4, s[34:35]
	s_sub_i32 s16, s99, s11
	s_ashr_i32 s17, s16, 31
	s_lshl_b64 s[16:17], s[16:17], 18
	s_add_u32 s16, s38, s16
	v_and_b32_e32 v9, 0x2000, v5
	v_mov_b32_e32 v1, v65
	v_mov_b32_e32 v3, v65
	v_mov_b32_e32 v5, v65
	s_addc_u32 s17, s39, s17
	v_lshl_add_u64 v[66:67], s[16:17], 0, v[64:65]
	v_lshl_add_u64 v[68:69], s[16:17], 0, v[0:1]
	v_lshl_add_u64 v[70:71], s[16:17], 0, v[2:3]
	v_lshl_add_u64 v[72:73], s[16:17], 0, v[4:5]
	s_add_u32 s16, s36, s18
	v_add_u32_e32 v8, 0, v8
	v_add_u32_e32 v9, 0, v9
	s_addc_u32 s17, s37, s19
	v_lshl_add_u64 v[74:75], s[16:17], 0, v[64:65]
	v_lshl_add_u64 v[76:77], s[16:17], 0, v[0:1]
	v_lshl_add_u64 v[78:79], s[16:17], 0, v[2:3]
	v_lshl_add_u64 v[80:81], s[16:17], 0, v[4:5]
	s_mov_b64 s[16:17], 0
	v_add_u32_e32 v64, 0x8000, v100
	v_add_u32_e32 v108, 0x9000, v100
	v_add_u32_e32 v109, 0xa000, v100
	v_add_u32_e32 v110, 0xb000, v100
	v_add_u32_e32 v111, 0xc000, v100
	v_add_u32_e32 v112, 0xd000, v100
	v_add_u32_e32 v113, 0xe000, v100
	v_add_u32_e32 v114, 0xf000, v100
	v_add_u32_e32 v115, v8, v7
	v_add_u32_e32 v116, v9, v7
	v_add_u32_e32 v117, v8, v6
	v_add_u32_e32 v118, v9, v6
	s_mov_b32 s11, 0
	v_mov_b32_e32 v0, 0
	v_mov_b32_e32 v2, v65
	v_mov_b32_e32 v8, 0
	v_mov_b32_e32 v9, v65
	v_mov_b32_e32 v10, v65
	v_mov_b32_e32 v11, v65
	v_mov_b32_e32 v4, 0
	v_mov_b32_e32 v6, v65
	v_mov_b32_e32 v7, v65
	v_mov_b32_e32 v12, 0
	v_mov_b32_e32 v13, v65
	v_mov_b32_e32 v14, v65
	v_mov_b32_e32 v15, v65
	v_mov_b32_e32 v16, 0
	v_mov_b32_e32 v17, v65
	v_mov_b32_e32 v18, v65
	v_mov_b32_e32 v19, v65
	v_mov_b32_e32 v24, 0
	v_mov_b32_e32 v25, v65
	v_mov_b32_e32 v26, v65
	v_mov_b32_e32 v27, v65
	v_mov_b32_e32 v20, 0
	v_mov_b32_e32 v21, v65
	v_mov_b32_e32 v22, v65
	v_mov_b32_e32 v23, v65
	v_mov_b32_e32 v28, 0
	v_mov_b32_e32 v29, v65
	v_mov_b32_e32 v30, v65
	v_mov_b32_e32 v31, v65
	v_mov_b32_e32 v32, 0
	v_mov_b32_e32 v33, v65
	v_mov_b32_e32 v34, v65
	v_mov_b32_e32 v35, v65
	v_mov_b32_e32 v40, 0
	v_mov_b32_e32 v41, v65
	v_mov_b32_e32 v42, v65
	v_mov_b32_e32 v43, v65
	v_mov_b32_e32 v36, 0
	v_mov_b32_e32 v37, v65
	v_mov_b32_e32 v38, v65
	v_mov_b32_e32 v39, v65
	v_mov_b32_e32 v44, 0
	v_mov_b32_e32 v45, v65
	v_mov_b32_e32 v46, v65
	v_mov_b32_e32 v47, v65
	v_mov_b32_e32 v48, 0
	v_mov_b32_e32 v49, v65
	v_mov_b32_e32 v50, v65
	v_mov_b32_e32 v51, v65
	v_mov_b32_e32 v56, 0
	v_mov_b32_e32 v57, v65
	v_mov_b32_e32 v58, v65
	v_mov_b32_e32 v59, v65
	v_mov_b32_e32 v52, 0
	v_mov_b32_e32 v53, v65
	v_mov_b32_e32 v54, v65
	v_mov_b32_e32 v55, v65
	v_mov_b32_e32 v60, 0
	v_mov_b32_e32 v61, v65
	v_mov_b32_e32 v62, v65
	v_mov_b32_e32 v63, v65
	s_nop 1
	v_readfirstlane_b32 s16, v66
	v_readfirstlane_b32 s17, v67
	v_readfirstlane_b32 s98, v74
	v_readfirstlane_b32 s99, v75
	v_readfirstlane_b32 s100, v100
	s_nop 1
	s_sub_u32 s16, s16, 0x80
	s_subb_u32 s17, s17, 0
	s_sub_u32 s98, s98, 0x80
	s_subb_u32 s99, s99, 0
	v_subrev_u32_e32 v66, s16, v66
	v_subrev_u32_e32 v68, s16, v68
	v_subrev_u32_e32 v70, s16, v70
	v_subrev_u32_e32 v72, s16, v72
	v_subrev_u32_e32 v74, s98, v74
	v_subrev_u32_e32 v76, s98, v76
	v_subrev_u32_e32 v78, s98, v78
	v_subrev_u32_e32 v80, s98, v80
	s_add_u32 s16, s16, 0x80
	s_addc_u32 s17, s17, 0x0
	s_add_u32 s98, s98, 0x13c0080
	s_addc_u32 s99, s99, 0x0
	s_branch .LBB0_1867
.LBB0_1866:
	ds_read_b128 v[82:85], v115 offset:32768
	ds_read_b128 v[86:89], v115 offset:34816
	ds_read_b128 v[90:93], v115 offset:36864
	ds_read_b128 v[94:97], v115 offset:38912
	ds_read_b128 v[120:123], v116 offset:49152
	ds_read_b128 v[124:127], v116 offset:51200
	ds_read_b128 v[128:131], v116 offset:53248
	ds_read_b128 v[132:135], v116 offset:55296
	ds_read_b128 v[136:139], v117 offset:32768
	ds_read_b128 v[140:143], v117 offset:34816
	ds_read_b128 v[144:147], v117 offset:36864
	ds_read_b128 v[148:151], v117 offset:38912
	ds_read_b128 v[152:155], v118 offset:49152
	ds_read_b128 v[156:159], v118 offset:51200
	ds_read_b128 v[160:163], v118 offset:53248
	ds_read_b128 v[164:167], v118 offset:55296
	s_add_i32 s11, s11, 2
	s_waitcnt lgkmcnt(0)
	v_mfma_f32_16x16x32_f16 v[0:3], v[120:123], v[82:85], v[0:3]
	v_mfma_f32_16x16x32_f16 v[4:7], v[124:127], v[82:85], v[4:7]
	v_mfma_f32_16x16x32_f16 v[8:11], v[128:131], v[82:85], v[8:11]
	v_mfma_f32_16x16x32_f16 v[12:15], v[132:135], v[82:85], v[12:15]
	v_mfma_f32_16x16x32_f16 v[16:19], v[120:123], v[86:89], v[16:19]
	v_mfma_f32_16x16x32_f16 v[20:23], v[124:127], v[86:89], v[20:23]
	v_mfma_f32_16x16x32_f16 v[24:27], v[128:131], v[86:89], v[24:27]
	v_mfma_f32_16x16x32_f16 v[28:31], v[132:135], v[86:89], v[28:31]
	v_mfma_f32_16x16x32_f16 v[82:85], v[120:123], v[90:93], v[32:35]
	v_mfma_f32_16x16x32_f16 v[86:89], v[124:127], v[90:93], v[36:39]
	v_mfma_f32_16x16x32_f16 v[168:171], v[128:131], v[90:93], v[40:43]
	v_mfma_f32_16x16x32_f16 v[90:93], v[132:135], v[90:93], v[44:47]
	v_mfma_f32_16x16x32_f16 v[120:123], v[120:123], v[94:97], v[48:51]
	v_mfma_f32_16x16x32_f16 v[124:127], v[124:127], v[94:97], v[52:55]
	v_mfma_f32_16x16x32_f16 v[128:131], v[128:131], v[94:97], v[56:59]
	v_mfma_f32_16x16x32_f16 v[94:97], v[132:135], v[94:97], v[60:63]
	v_mfma_f32_16x16x32_f16 v[60:63], v[152:155], v[136:139], v[0:3]
	v_mfma_f32_16x16x32_f16 v[52:55], v[156:159], v[136:139], v[4:7]
	v_mfma_f32_16x16x32_f16 v[56:59], v[160:163], v[136:139], v[8:11]
	v_mfma_f32_16x16x32_f16 v[48:51], v[164:167], v[136:139], v[12:15]
	v_mfma_f32_16x16x32_f16 v[44:47], v[152:155], v[140:143], v[16:19]
	v_mfma_f32_16x16x32_f16 v[36:39], v[156:159], v[140:143], v[20:23]
	v_mfma_f32_16x16x32_f16 v[40:43], v[160:163], v[140:143], v[24:27]
	v_mfma_f32_16x16x32_f16 v[32:35], v[164:167], v[140:143], v[28:31]
	v_mfma_f32_16x16x32_f16 v[28:31], v[152:155], v[144:147], v[82:85]
	v_mfma_f32_16x16x32_f16 v[20:23], v[156:159], v[144:147], v[86:89]
	v_mfma_f32_16x16x32_f16 v[24:27], v[160:163], v[144:147], v[168:171]
	v_mfma_f32_16x16x32_f16 v[16:19], v[164:167], v[144:147], v[90:93]
	v_mfma_f32_16x16x32_f16 v[12:15], v[152:155], v[148:151], v[120:123]
	v_mfma_f32_16x16x32_f16 v[4:7], v[156:159], v[148:151], v[124:127]
	v_mfma_f32_16x16x32_f16 v[8:11], v[160:163], v[148:151], v[128:131]
	v_mfma_f32_16x16x32_f16 v[0:3], v[164:167], v[148:151], v[94:97]
	s_andn2_b64 vcc, exec, s[18:19]
	s_cbranch_vccz .LBB0_1864
.LBB0_1867:
	s_waitcnt vmcnt(0)
	s_waitcnt vmcnt(0) lgkmcnt(0)
	s_barrier
	s_add_i32 m0, s100, 0x8000
	s_nop 0
	global_load_lds_dwordx4 v66, s[16:17]
	s_add_i32 m0, s100, 0x9000
	s_nop 0
	global_load_lds_dwordx4 v68, s[16:17]
	s_add_i32 m0, s100, 0xa000
	s_nop 0
	global_load_lds_dwordx4 v70, s[16:17]
	s_add_i32 m0, s100, 0xb000
	s_nop 0
	global_load_lds_dwordx4 v72, s[16:17]
	s_add_i32 m0, s100, 0xc000
	s_nop 0
	global_load_lds_dwordx4 v74, s[98:99]
	s_add_i32 m0, s100, 0xd000
	s_nop 0
	global_load_lds_dwordx4 v76, s[98:99]
	s_add_i32 m0, s100, 0xe000
	s_nop 0
	global_load_lds_dwordx4 v78, s[98:99]
	s_add_i32 m0, s100, 0xf000
	s_nop 0
	global_load_lds_dwordx4 v80, s[98:99]
	s_add_u32 s16, s16, 0x80
	s_addc_u32 s17, s17, 0
	s_add_u32 s98, s98, 0x80
	s_addc_u32 s99, s99, 0
	ds_read_b128 v[120:123], v115
	ds_read_b128 v[124:127], v115 offset:2048
	ds_read_b128 v[128:131], v115 offset:4096
	ds_read_b128 v[132:135], v115 offset:6144
	ds_read_b128 v[136:139], v116 offset:16384
	ds_read_b128 v[140:143], v116 offset:18432
	ds_read_b128 v[144:147], v116 offset:20480
	ds_read_b128 v[148:151], v116 offset:22528
	ds_read_b128 v[152:155], v117
	ds_read_b128 v[156:159], v117 offset:2048
	ds_read_b128 v[160:163], v117 offset:4096
	ds_read_b128 v[164:167], v117 offset:6144
	ds_read_b128 v[168:171], v118 offset:16384
	ds_read_b128 v[176:179], v118 offset:18432
	ds_read_b128 v[180:183], v118 offset:20480
	ds_read_b128 v[184:187], v118 offset:22528
	s_waitcnt lgkmcnt(0)
	v_mfma_f32_16x16x32_f16 v[60:63], v[136:139], v[120:123], v[60:63]
	v_mfma_f32_16x16x32_f16 v[52:55], v[140:143], v[120:123], v[52:55]
	v_mfma_f32_16x16x32_f16 v[56:59], v[144:147], v[120:123], v[56:59]
	v_mfma_f32_16x16x32_f16 v[48:51], v[148:151], v[120:123], v[48:51]
	v_mfma_f32_16x16x32_f16 v[44:47], v[136:139], v[124:127], v[44:47]
	v_mfma_f32_16x16x32_f16 v[36:39], v[140:143], v[124:127], v[36:39]
	v_mfma_f32_16x16x32_f16 v[40:43], v[144:147], v[124:127], v[40:43]
	v_mfma_f32_16x16x32_f16 v[32:35], v[148:151], v[124:127], v[32:35]
	v_mfma_f32_16x16x32_f16 v[120:123], v[136:139], v[128:131], v[28:31]
	v_mfma_f32_16x16x32_f16 v[124:127], v[140:143], v[128:131], v[20:23]
	v_mfma_f32_16x16x32_f16 v[188:191], v[144:147], v[128:131], v[24:27]
	v_mfma_f32_16x16x32_f16 v[128:131], v[148:151], v[128:131], v[16:19]
	v_mfma_f32_16x16x32_f16 v[136:139], v[136:139], v[132:135], v[12:15]
	v_mfma_f32_16x16x32_f16 v[140:143], v[140:143], v[132:135], v[4:7]
	v_mfma_f32_16x16x32_f16 v[144:147], v[144:147], v[132:135], v[8:11]
	v_mfma_f32_16x16x32_f16 v[132:135], v[148:151], v[132:135], v[0:3]
	v_mfma_f32_16x16x32_f16 v[0:3], v[168:171], v[152:155], v[60:63]
	v_mfma_f32_16x16x32_f16 v[4:7], v[176:179], v[152:155], v[52:55]
	v_mfma_f32_16x16x32_f16 v[8:11], v[180:183], v[152:155], v[56:59]
	v_mfma_f32_16x16x32_f16 v[12:15], v[184:187], v[152:155], v[48:51]
	v_mfma_f32_16x16x32_f16 v[16:19], v[168:171], v[156:159], v[44:47]
	v_mfma_f32_16x16x32_f16 v[20:23], v[176:179], v[156:159], v[36:39]
	v_mfma_f32_16x16x32_f16 v[24:27], v[180:183], v[156:159], v[40:43]
	v_mfma_f32_16x16x32_f16 v[28:31], v[184:187], v[156:159], v[32:35]
	v_mfma_f32_16x16x32_f16 v[32:35], v[168:171], v[160:163], v[120:123]
	v_mfma_f32_16x16x32_f16 v[36:39], v[176:179], v[160:163], v[124:127]
	v_mfma_f32_16x16x32_f16 v[40:43], v[180:183], v[160:163], v[188:191]
	v_mfma_f32_16x16x32_f16 v[44:47], v[184:187], v[160:163], v[128:131]
	v_mfma_f32_16x16x32_f16 v[48:51], v[168:171], v[164:167], v[136:139]
	v_mfma_f32_16x16x32_f16 v[52:55], v[176:179], v[164:167], v[140:143]
	v_mfma_f32_16x16x32_f16 v[56:59], v[180:183], v[164:167], v[144:147]
	v_mfma_f32_16x16x32_f16 v[60:63], v[184:187], v[164:167], v[132:135]
	s_waitcnt vmcnt(0)
	s_cmp_gt_u32 s11, 13
	s_cselect_b64 s[18:19], -1, 0
	s_and_b64 vcc, exec, s[18:19]
	s_waitcnt vmcnt(0)
	s_barrier
	s_cbranch_vccnz .LBB0_1866
	s_mov_b32 m0, s100
	s_nop 0
	global_load_lds_dwordx4 v66, s[16:17]
	s_add_i32 m0, s100, 0x1000
	s_nop 0
	global_load_lds_dwordx4 v68, s[16:17]
	s_add_i32 m0, s100, 0x2000
	s_nop 0
	global_load_lds_dwordx4 v70, s[16:17]
	s_add_i32 m0, s100, 0x3000
	s_nop 0
	global_load_lds_dwordx4 v72, s[16:17]
	s_add_i32 m0, s100, 0x4000
	s_nop 0
	global_load_lds_dwordx4 v74, s[98:99]
	s_add_i32 m0, s100, 0x5000
	s_nop 0
	global_load_lds_dwordx4 v76, s[98:99]
	s_add_i32 m0, s100, 0x6000
	s_nop 0
	global_load_lds_dwordx4 v78, s[98:99]
	s_add_i32 m0, s100, 0x7000
	s_nop 0
	global_load_lds_dwordx4 v80, s[98:99]
	s_add_u32 s16, s16, 0x80
	s_addc_u32 s17, s17, 0
	s_add_u32 s98, s98, 0x80
	s_addc_u32 s99, s99, 0
	s_branch .LBB0_1866

.Lto_j_b5:
	s_mul_i32 s98, s98, 17
	s_add_u32 s98, s98, s99
	s_lshl_b32 s99, s98, 3
	s_or_b32 s99, s99, s13
	s_mul_hi_i32 s8, s98, 0x78787879
	s_lshr_b32 s9, s8, 31
	s_ashr_i32 s20, s8, 3
	s_add_i32 s20, s20, s9
	v_mov_b32_e32 v0, v174
	s_mul_i32 s8, s20, 0xffffffef
	s_add_i32 s8, s8, s98
	v_bfe_u32 v2, v0, 1, 3
	v_lshrrev_b32_e32 v3, 4, v0
	s_waitcnt vmcnt(5)
	v_bfe_u32 v4, v0, 4, 2
	v_lshlrev_b32_e32 v5, 7, v0
	v_and_b32_e32 v6, 0x780, v5
	v_bitop3_b32 v3, v3, v2, 3 bitop3:0x6c
	v_bitop3_b32 v2, v4, v2, 4 bitop3:0x36
	s_lshl_b32 s8, s8, 3
	v_lshl_or_b32 v7, v3, 4, v6
	v_lshl_or_b32 v6, v2, 4, v6
	v_lshlrev_b32_e32 v2, 6, v0
	s_or_b32 s21, s8, s13
	v_and_b32_e32 v8, 0xffffe000, v2
	v_lshlrev_b32_e32 v2, 4, v0
	s_mul_i32 s8, s21, 0xb0000
	v_lshrrev_b32_e32 v1, 3, v0
	v_add_u32_e32 v100, 0, v2
	s_mul_hi_i32 s9, s21, 0xb0000
	s_add_u32 s8, s42, s8
	v_mul_lo_u32 v1, v1, s18
	v_xor_b32_e32 v0, v2, v0
	v_readfirstlane_b32 s24, v100
	v_add_u32_e32 v101, 0x1000, v100
	s_addc_u32 s9, s43, s9
	v_and_or_b32 v64, v0, s19, v1
	s_mov_b32 m0, s24
	v_readfirstlane_b32 s24, v101
	v_add_u32_e32 v102, 0x2000, v100
	global_load_lds_dwordx4 v64, s[8:9]
	v_add_u32_e32 v0, 0x2c000, v64
	s_mov_b32 m0, s24
	v_readfirstlane_b32 s24, v102
	v_add_u32_e32 v103, 0x3000, v100
	global_load_lds_dwordx4 v0, s[8:9]
	v_add_u32_e32 v2, 0x58000, v64
	s_mov_b32 m0, s24
	v_readfirstlane_b32 s24, v103
	s_mul_i32 s23, s20, 0xb0000
	global_load_lds_dwordx4 v2, s[8:9]
	v_add_u32_e32 v4, 0x84000, v64
	s_mov_b32 m0, s24
	v_add_u32_e32 v104, 0x4000, v100
	s_mul_hi_i32 s22, s20, 0xb0000
	s_add_u32 s10, s88, s23
	global_load_lds_dwordx4 v4, s[8:9]
	v_readfirstlane_b32 s8, v104
	v_add_u32_e32 v105, 0x5000, v100
	s_addc_u32 s11, s89, s22
	s_mov_b32 m0, s8
	v_readfirstlane_b32 s8, v105
	v_add_u32_e32 v106, 0x6000, v100
	global_load_lds_dwordx4 v64, s[10:11]
	s_mov_b32 m0, s8
	v_readfirstlane_b32 s8, v106
	v_add_u32_e32 v107, 0x7000, v100
	global_load_lds_dwordx4 v0, s[10:11]
	s_mov_b32 m0, s8
	v_readfirstlane_b32 s8, v107
	global_load_lds_dwordx4 v2, s[10:11]
	s_mov_b32 m0, s8
	s_mul_i32 s8, s20, 0x88
	global_load_lds_dwordx4 v4, s[10:11]
	s_sub_i32 s8, s99, s8
	s_mul_hi_i32 s9, s8, 0xb0000
	s_mul_i32 s8, s8, 0xb0000
	s_add_u32 s8, s42, s8
	v_and_b32_e32 v9, 0x2000, v5
	v_mov_b32_e32 v1, v65
	v_mov_b32_e32 v3, v65
	v_mov_b32_e32 v5, v65
	s_addc_u32 s9, s43, s9
	v_lshl_add_u64 v[66:67], s[8:9], 0, v[64:65]
	v_lshl_add_u64 v[68:69], s[8:9], 0, v[0:1]
	v_lshl_add_u64 v[70:71], s[8:9], 0, v[2:3]
	v_lshl_add_u64 v[72:73], s[8:9], 0, v[4:5]
	s_add_u32 s8, s36, s23
	v_add_u32_e32 v8, 0, v8
	v_add_u32_e32 v9, 0, v9
	s_addc_u32 s9, s37, s22
	v_lshl_add_u64 v[74:75], s[8:9], 0, v[64:65]
	v_lshl_add_u64 v[76:77], s[8:9], 0, v[0:1]
	v_lshl_add_u64 v[78:79], s[8:9], 0, v[2:3]
	v_lshl_add_u64 v[80:81], s[8:9], 0, v[4:5]
	s_mov_b64 s[8:9], 0
	v_add_u32_e32 v64, 0x8000, v100
	v_add_u32_e32 v108, 0x9000, v100
	v_add_u32_e32 v109, 0xa000, v100
	v_add_u32_e32 v110, 0xb000, v100
	v_add_u32_e32 v111, 0xc000, v100
	v_add_u32_e32 v112, 0xd000, v100
	v_add_u32_e32 v113, 0xe000, v100
	v_add_u32_e32 v114, 0xf000, v100
	v_add_u32_e32 v115, v8, v7
	v_add_u32_e32 v116, v9, v7
	v_add_u32_e32 v117, v8, v6
	v_add_u32_e32 v118, v9, v6
	s_mov_b32 s22, 0
	v_mov_b32_e32 v0, 0
	v_mov_b32_e32 v2, v65
	v_mov_b32_e32 v4, 0
	v_mov_b32_e32 v6, v65
	v_mov_b32_e32 v7, v65
	v_mov_b32_e32 v8, 0
	v_mov_b32_e32 v9, v65
	v_mov_b32_e32 v10, v65
	v_mov_b32_e32 v11, v65
	v_mov_b32_e32 v12, 0
	v_mov_b32_e32 v13, v65
	v_mov_b32_e32 v14, v65
	v_mov_b32_e32 v15, v65
	v_mov_b32_e32 v16, 0
	v_mov_b32_e32 v17, v65
	v_mov_b32_e32 v18, v65
	v_mov_b32_e32 v19, v65
	v_mov_b32_e32 v20, 0
	v_mov_b32_e32 v21, v65
	v_mov_b32_e32 v22, v65
	v_mov_b32_e32 v23, v65
	v_mov_b32_e32 v24, 0
	v_mov_b32_e32 v25, v65
	v_mov_b32_e32 v26, v65
	v_mov_b32_e32 v27, v65
	v_mov_b32_e32 v28, 0
	v_mov_b32_e32 v29, v65
	v_mov_b32_e32 v30, v65
	v_mov_b32_e32 v31, v65
	v_mov_b32_e32 v32, 0
	v_mov_b32_e32 v33, v65
	v_mov_b32_e32 v34, v65
	v_mov_b32_e32 v35, v65
	v_mov_b32_e32 v36, 0
	v_mov_b32_e32 v37, v65
	v_mov_b32_e32 v38, v65
	v_mov_b32_e32 v39, v65
	v_mov_b32_e32 v40, 0
	v_mov_b32_e32 v41, v65
	v_mov_b32_e32 v42, v65
	v_mov_b32_e32 v43, v65
	v_mov_b32_e32 v44, 0
	v_mov_b32_e32 v45, v65
	v_mov_b32_e32 v46, v65
	v_mov_b32_e32 v47, v65
	v_mov_b32_e32 v48, 0
	v_mov_b32_e32 v49, v65
	v_mov_b32_e32 v50, v65
	v_mov_b32_e32 v51, v65
	v_mov_b32_e32 v52, 0
	v_mov_b32_e32 v53, v65
	s_waitcnt vmcnt(0)
	v_mov_b32_e32 v54, v65
	v_mov_b32_e32 v55, v65
	v_mov_b32_e32 v56, 0
	v_mov_b32_e32 v57, v65
	v_mov_b32_e32 v58, v65
	v_mov_b32_e32 v59, v65
	v_mov_b32_e32 v60, 0
	v_mov_b32_e32 v61, v65
	v_mov_b32_e32 v62, v65
	v_mov_b32_e32 v63, v65
	s_nop 1
	v_readfirstlane_b32 s8, v66
	v_readfirstlane_b32 s9, v67
	v_readfirstlane_b32 s98, v74
	v_readfirstlane_b32 s99, v75
	v_readfirstlane_b32 s100, v100
	s_nop 1
	s_sub_u32 s8, s8, 0x80
	s_subb_u32 s9, s9, 0
	s_sub_u32 s98, s98, 0x80
	s_subb_u32 s99, s99, 0
	v_subrev_u32_e32 v66, s8, v66
	v_subrev_u32_e32 v68, s8, v68
	v_subrev_u32_e32 v70, s8, v70
	v_subrev_u32_e32 v72, s8, v72
	v_subrev_u32_e32 v74, s98, v74
	v_subrev_u32_e32 v76, s98, v76
	v_subrev_u32_e32 v78, s98, v78
	v_subrev_u32_e32 v80, s98, v80
	s_add_u32 s8, s8, 0x80
	s_addc_u32 s9, s9, 0x0
	s_add_u32 s98, s98, 0x1ec0080
	s_addc_u32 s99, s99, 0x0
	s_branch .LBB0_1936
.LBB0_1935:
	ds_read_b128 v[82:85], v115 offset:32768
	ds_read_b128 v[86:89], v115 offset:34816
	ds_read_b128 v[90:93], v115 offset:36864
	ds_read_b128 v[94:97], v115 offset:38912
	ds_read_b128 v[120:123], v116 offset:49152
	ds_read_b128 v[124:127], v116 offset:51200
	ds_read_b128 v[128:131], v116 offset:53248
	ds_read_b128 v[132:135], v116 offset:55296
	ds_read_b128 v[136:139], v117 offset:32768
	ds_read_b128 v[140:143], v117 offset:34816
	ds_read_b128 v[144:147], v117 offset:36864
	ds_read_b128 v[148:151], v117 offset:38912
	ds_read_b128 v[152:155], v118 offset:49152
	ds_read_b128 v[156:159], v118 offset:51200
	ds_read_b128 v[160:163], v118 offset:53248
	ds_read_b128 v[164:167], v118 offset:55296
	s_add_i32 s22, s22, 2
	s_waitcnt lgkmcnt(0)
	v_mfma_f32_16x16x32_f16 v[0:3], v[120:123], v[82:85], v[0:3]
	v_mfma_f32_16x16x32_f16 v[4:7], v[124:127], v[82:85], v[4:7]
	v_mfma_f32_16x16x32_f16 v[8:11], v[128:131], v[82:85], v[8:11]
	v_mfma_f32_16x16x32_f16 v[12:15], v[132:135], v[82:85], v[12:15]
	v_mfma_f32_16x16x32_f16 v[16:19], v[120:123], v[86:89], v[16:19]
	v_mfma_f32_16x16x32_f16 v[20:23], v[124:127], v[86:89], v[20:23]
	v_mfma_f32_16x16x32_f16 v[24:27], v[128:131], v[86:89], v[24:27]
	v_mfma_f32_16x16x32_f16 v[28:31], v[132:135], v[86:89], v[28:31]
	v_mfma_f32_16x16x32_f16 v[82:85], v[120:123], v[90:93], v[32:35]
	v_mfma_f32_16x16x32_f16 v[86:89], v[124:127], v[90:93], v[36:39]
	v_mfma_f32_16x16x32_f16 v[168:171], v[128:131], v[90:93], v[40:43]
	v_mfma_f32_16x16x32_f16 v[90:93], v[132:135], v[90:93], v[44:47]
	v_mfma_f32_16x16x32_f16 v[120:123], v[120:123], v[94:97], v[48:51]
	v_mfma_f32_16x16x32_f16 v[124:127], v[124:127], v[94:97], v[52:55]
	v_mfma_f32_16x16x32_f16 v[128:131], v[128:131], v[94:97], v[56:59]
	v_mfma_f32_16x16x32_f16 v[94:97], v[132:135], v[94:97], v[60:63]
	v_mfma_f32_16x16x32_f16 v[60:63], v[152:155], v[136:139], v[0:3]
	v_mfma_f32_16x16x32_f16 v[56:59], v[156:159], v[136:139], v[4:7]
	v_mfma_f32_16x16x32_f16 v[52:55], v[160:163], v[136:139], v[8:11]
	v_mfma_f32_16x16x32_f16 v[48:51], v[164:167], v[136:139], v[12:15]
	v_mfma_f32_16x16x32_f16 v[44:47], v[152:155], v[140:143], v[16:19]
	v_mfma_f32_16x16x32_f16 v[40:43], v[156:159], v[140:143], v[20:23]
	v_mfma_f32_16x16x32_f16 v[36:39], v[160:163], v[140:143], v[24:27]
	v_mfma_f32_16x16x32_f16 v[32:35], v[164:167], v[140:143], v[28:31]
	v_mfma_f32_16x16x32_f16 v[28:31], v[152:155], v[144:147], v[82:85]
	v_mfma_f32_16x16x32_f16 v[24:27], v[156:159], v[144:147], v[86:89]
	v_mfma_f32_16x16x32_f16 v[20:23], v[160:163], v[144:147], v[168:171]
	v_mfma_f32_16x16x32_f16 v[16:19], v[164:167], v[144:147], v[90:93]
	v_mfma_f32_16x16x32_f16 v[12:15], v[152:155], v[148:151], v[120:123]
	v_mfma_f32_16x16x32_f16 v[8:11], v[156:159], v[148:151], v[124:127]
	v_mfma_f32_16x16x32_f16 v[4:7], v[160:163], v[148:151], v[128:131]
	v_mfma_f32_16x16x32_f16 v[0:3], v[164:167], v[148:151], v[94:97]
	s_andn2_b64 vcc, exec, s[10:11]
	s_cbranch_vccz .LBB0_1933
.LBB0_1936:
	s_waitcnt vmcnt(0)
	s_waitcnt lgkmcnt(0)
	s_barrier
	s_add_i32 m0, s100, 0x8000
	s_nop 0
	global_load_lds_dwordx4 v66, s[8:9]
	s_add_i32 m0, s100, 0x9000
	s_nop 0
	global_load_lds_dwordx4 v68, s[8:9]
	s_add_i32 m0, s100, 0xa000
	s_nop 0
	global_load_lds_dwordx4 v70, s[8:9]
	s_add_i32 m0, s100, 0xb000
	s_nop 0
	global_load_lds_dwordx4 v72, s[8:9]
	s_add_i32 m0, s100, 0xc000
	s_nop 0
	global_load_lds_dwordx4 v74, s[98:99]
	s_add_i32 m0, s100, 0xd000
	s_nop 0
	global_load_lds_dwordx4 v76, s[98:99]
	s_add_i32 m0, s100, 0xe000
	s_nop 0
	global_load_lds_dwordx4 v78, s[98:99]
	s_add_i32 m0, s100, 0xf000
	s_nop 0
	global_load_lds_dwordx4 v80, s[98:99]
	s_add_u32 s8, s8, 0x80
	s_addc_u32 s9, s9, 0
	s_add_u32 s98, s98, 0x80
	s_addc_u32 s99, s99, 0
	ds_read_b128 v[120:123], v115
	ds_read_b128 v[124:127], v115 offset:2048
	ds_read_b128 v[128:131], v115 offset:4096
	ds_read_b128 v[132:135], v115 offset:6144
	ds_read_b128 v[136:139], v116 offset:16384
	ds_read_b128 v[140:143], v116 offset:18432
	ds_read_b128 v[144:147], v116 offset:20480
	ds_read_b128 v[148:151], v116 offset:22528
	ds_read_b128 v[152:155], v117
	ds_read_b128 v[156:159], v117 offset:2048
	ds_read_b128 v[160:163], v117 offset:4096
	ds_read_b128 v[164:167], v117 offset:6144
	ds_read_b128 v[168:171], v118 offset:16384
	ds_read_b128 v[176:179], v118 offset:18432
	ds_read_b128 v[180:183], v118 offset:20480
	ds_read_b128 v[184:187], v118 offset:22528
	s_waitcnt lgkmcnt(0)
	v_mfma_f32_16x16x32_f16 v[60:63], v[136:139], v[120:123], v[60:63]
	v_mfma_f32_16x16x32_f16 v[56:59], v[140:143], v[120:123], v[56:59]
	v_mfma_f32_16x16x32_f16 v[52:55], v[144:147], v[120:123], v[52:55]
	v_mfma_f32_16x16x32_f16 v[48:51], v[148:151], v[120:123], v[48:51]
	v_mfma_f32_16x16x32_f16 v[44:47], v[136:139], v[124:127], v[44:47]
	v_mfma_f32_16x16x32_f16 v[40:43], v[140:143], v[124:127], v[40:43]
	v_mfma_f32_16x16x32_f16 v[36:39], v[144:147], v[124:127], v[36:39]
	v_mfma_f32_16x16x32_f16 v[32:35], v[148:151], v[124:127], v[32:35]
	v_mfma_f32_16x16x32_f16 v[120:123], v[136:139], v[128:131], v[28:31]
	v_mfma_f32_16x16x32_f16 v[124:127], v[140:143], v[128:131], v[24:27]
	v_mfma_f32_16x16x32_f16 v[188:191], v[144:147], v[128:131], v[20:23]
	v_mfma_f32_16x16x32_f16 v[128:131], v[148:151], v[128:131], v[16:19]
	v_mfma_f32_16x16x32_f16 v[136:139], v[136:139], v[132:135], v[12:15]
	v_mfma_f32_16x16x32_f16 v[140:143], v[140:143], v[132:135], v[8:11]
	v_mfma_f32_16x16x32_f16 v[144:147], v[144:147], v[132:135], v[4:7]
	v_mfma_f32_16x16x32_f16 v[132:135], v[148:151], v[132:135], v[0:3]
	v_mfma_f32_16x16x32_f16 v[0:3], v[168:171], v[152:155], v[60:63]
	v_mfma_f32_16x16x32_f16 v[4:7], v[176:179], v[152:155], v[56:59]
	v_mfma_f32_16x16x32_f16 v[8:11], v[180:183], v[152:155], v[52:55]
	v_mfma_f32_16x16x32_f16 v[12:15], v[184:187], v[152:155], v[48:51]
	v_mfma_f32_16x16x32_f16 v[16:19], v[168:171], v[156:159], v[44:47]
	v_mfma_f32_16x16x32_f16 v[20:23], v[176:179], v[156:159], v[40:43]
	v_mfma_f32_16x16x32_f16 v[24:27], v[180:183], v[156:159], v[36:39]
	v_mfma_f32_16x16x32_f16 v[28:31], v[184:187], v[156:159], v[32:35]
	v_mfma_f32_16x16x32_f16 v[32:35], v[168:171], v[160:163], v[120:123]
	v_mfma_f32_16x16x32_f16 v[36:39], v[176:179], v[160:163], v[124:127]
	v_mfma_f32_16x16x32_f16 v[40:43], v[180:183], v[160:163], v[188:191]
	v_mfma_f32_16x16x32_f16 v[44:47], v[184:187], v[160:163], v[128:131]
	v_mfma_f32_16x16x32_f16 v[48:51], v[168:171], v[164:167], v[136:139]
	v_mfma_f32_16x16x32_f16 v[52:55], v[176:179], v[164:167], v[140:143]
	v_mfma_f32_16x16x32_f16 v[56:59], v[180:183], v[164:167], v[144:147]
	v_mfma_f32_16x16x32_f16 v[60:63], v[184:187], v[164:167], v[132:135]
	s_waitcnt vmcnt(0)
	s_cmp_gt_u32 s22, 41
	s_cselect_b64 s[10:11], -1, 0
	s_and_b64 vcc, exec, s[10:11]
	s_waitcnt vmcnt(0)
	s_barrier
	s_cbranch_vccnz .LBB0_1935
	s_mov_b32 m0, s100
	s_nop 0
	global_load_lds_dwordx4 v66, s[8:9]
	s_add_i32 m0, s100, 0x1000
	s_nop 0
	global_load_lds_dwordx4 v68, s[8:9]
	s_add_i32 m0, s100, 0x2000
	s_nop 0
	global_load_lds_dwordx4 v70, s[8:9]
	s_add_i32 m0, s100, 0x3000
	s_nop 0
	global_load_lds_dwordx4 v72, s[8:9]
	s_add_i32 m0, s100, 0x4000
	s_nop 0
	global_load_lds_dwordx4 v74, s[98:99]
	s_add_i32 m0, s100, 0x5000
	s_nop 0
	global_load_lds_dwordx4 v76, s[98:99]
	s_add_i32 m0, s100, 0x6000
	s_nop 0
	global_load_lds_dwordx4 v78, s[98:99]
	s_add_i32 m0, s100, 0x7000
	s_nop 0
	global_load_lds_dwordx4 v80, s[98:99]
	s_add_u32 s8, s8, 0x80
	s_addc_u32 s9, s9, 0
	s_add_u32 s98, s98, 0x80
	s_addc_u32 s99, s99, 0
	s_branch .LBB0_1935
